# v26 + X-row LDS buffer XOR swizzle (no 8-way bank conflict) + extra-row MFMAs accumulate in place
# speedup vs baseline: 1.0152x; 1.0152x over previous
; #define PG8_STAGE(bufoff, gbase, voff) do { _Pragma("unroll") for (int _i = 0; _i < 2; ++_i) glds16_s((voff)[_i], (const void*)(gbase), ldsbase + (unsigned)((bufoff) + _i * 8192) + ldsw); } while (0)
; template <class Epi, class Sched, bool HM = false>
; __device__ __forceinline__ void gemm_phase(PG8_LAS unsigned char* lds, const Gemm g, const Sched& S, const Epi& E) {
;     ...
;     for (int i = 0; i < 2; ++i) { int R, C; stage_rc(tid * 16 + i * 8192, R, C); const int Rb = Epi::PERM ? ((R & ~31) + perm32(R & 31)) : R;
;         voffA[i] = (unsigned)(R * g.lda + C) * 2u; voffB[i] = (unsigned)(Rb * g.ldb + C) * 2u; }
;     const unsigned voffX = (unsigned)((4 * (wid & 3) + (lane >> 4)) * g.lda + 8 * (lane & 15)) * 2u;
;     const size_t kstep = (size_t)(BK * 2);
;     const size_t hstepA = (size_t)HALF * g.lda * 2, hstepB = (size_t)HALF * g.ldb * 2;
;     const size_t tstepA = (size_t)(HM ? HALF : g.pms) * g.lda * 2, tstepB = 2 * hstepB, xstep = 2 * hstepA; const bool hasx = g.pms != BM;
;     const unsigned ldsw = (unsigned)wid * 1024u, ldsx = (unsigned)(wid & 3) * 1024u;
;     const unsigned ldsbase = (unsigned)__builtin_amdgcn_readfirstlane((int)(unsigned)(__UINTPTR_TYPE__)lds);
;     const int aoff = lds_byte(wr * 64 + fr, fq * 8), boff = lds_byte(wc * 32 + fr, fq * 8);
;     const int xoff = XOFF + fr * 256 + fq * 16;
;     ...
;     Unit cur, nxt; int ui = 0;
;     if (!S.next(0, cur)) return;
;     f32x4 acc[2][2][4][2]; f32x4 accx[2];
; #pragma unroll
;     for (int a = 0; a < 2; ++a)
; #pragma unroll
;         for (int b = 0; b < 2; ++b)
; #pragma unroll
;             for (int m = 0; m < 4; ++m)
; #pragma unroll
;                 for (int n = 0; n < 2; ++n) acc[a][b][m][n] = (f32x4){0.f, 0.f, 0.f, 0.f};
;     accx[0] = (f32x4){0.f, 0.f, 0.f, 0.f}; accx[1] = accx[0];
;     bf16x8 At[4][2], B0[2][2], B1[2][2], Ax[2];
;     const char* cA = PG8_APTR(cur); const char* cB = PG8_BPTR(cur);
;     S.a_ready(cur);
;     PG8_STAGE(PG8_SB(0, 0), cB, voffB); PG8_STAGE(PG8_SB(0, 1), cB + hstepB, voffB); PG8_STAGE(PG8_SA(0, 0), cA, voffA); PG8_STAGEX(0, cA + xstep); PG8_STAGE(PG8_SA(0, 1), cA + hstepA, voffA);
;     if (wr == 1) PG8_BAR;
;     PG8_WAIT_V(2); PG8_BAR;
;     PG8_STAGE(PG8_SB(1, 0), cB + kstep, voffB); PG8_STAGE(PG8_SA(1, 0), cA + kstep, voffA); PG8_STAGE(PG8_SB(1, 1), cB + hstepB + kstep, voffB);
;     PG8_WAIT_V(6); PG8_BAR;
.LBB0_237:
	s_mov_b64 s[0:1], s[30:31]
	s_mov_b64 s[4:5], s[30:31]
	s_mov_b64 s[8:9], s[30:31]
	s_waitcnt vmcnt(0)
	v_mov_b32_e32 v4, v0
	s_andn2_b64 vcc, exec, s[96:97]
	v_readfirstlane_b32 s20, v4
	s_cbranch_vccnz .LBB0_236
	v_bfe_i32 v7, v4, 27, 1
	v_lshlrev_b32_e32 v5, 4, v4
	v_lshrrev_b32_e32 v7, 22, v7
	v_add_u32_e32 v7, v5, v7
	v_and_b32_e32 v7, 0xfffffc00, v7
	v_sub_u32_e32 v7, v5, v7
	v_ashrrev_i32_e32 v6, 31, v4
	v_lshrrev_b32_e32 v8, 4, v7
	v_lshrrev_b32_e32 v6, 26, v6
	v_bitop3_b32 v7, v8, v7, 32 bitop3:0x6c
	v_add_u32_e32 v6, v4, v6
	v_ashrrev_i32_e32 v9, 31, v7
	v_ashrrev_i32_e32 v6, 6, v6
	v_lshrrev_b32_e32 v9, 26, v9
	v_lshlrev_b32_e32 v8, 3, v6
	v_add_u32_e32 v9, v7, v9
	v_and_b32_e32 v8, -16, v8
	v_ashrrev_i32_e32 v10, 6, v9
	v_and_b32_e32 v9, 0xc0, v9
	s_add_u32 s13, s0, 0x1a1e4000
	v_add_u32_e32 v8, v10, v8
	v_sub_u32_e32 v7, v7, v9
	s_addc_u32 s14, s1, 0
	v_lshlrev_b32_e32 v6, 5, v6
	v_ashrrev_i16_sdwa v7, v1, sext(v7) dst_sel:DWORD dst_unused:UNUSED_PAD src0_sel:DWORD src1_sel:BYTE_0
	v_lshlrev_b32_e32 v9, 1, v8
	v_lshrrev_b32_e32 v11, 2, v8
	v_and_b32_e32 v10, 3, v10
	s_mov_b32 s1, 0x3fffe0
	v_and_b32_e32 v6, 32, v6
	v_bfe_i32 v7, v7, 0, 16
	v_and_b32_e32 v9, 24, v9
	v_and_b32_e32 v11, 4, v11
	v_and_or_b32 v10, v8, s1, v10
	v_or3_b32 v9, v10, v11, v9
	v_add_lshl_u32 v6, v6, v7, 1
	v_add_u32_e32 v5, 0x2000, v5
	v_lshl_add_u32 v225, v8, 12, v6
	v_lshl_add_u32 v226, v9, 10, v6
	v_ashrrev_i32_e32 v6, 31, v5
	v_lshrrev_b32_e32 v6, 22, v6
	v_add_u32_e32 v6, v5, v6
	v_ashrrev_i32_e32 v6, 10, v6
	v_mul_i32_i24_e32 v7, 0x400, v6
	v_sub_u32_e32 v5, v5, v7
	v_lshrrev_b32_e32 v7, 4, v5
	v_bitop3_b32 v5, v7, v5, 32 bitop3:0x6c
	v_ashrrev_i32_e32 v8, 31, v5
	v_lshrrev_b32_e32 v8, 26, v8
	s_add_u32 s15, s4, 0x15aa0000
	v_lshlrev_b32_e32 v7, 3, v6
	v_add_u32_e32 v8, v5, v8
	s_addc_u32 s16, s5, 0
	s_ashr_i32 s0, s20, 6
	v_and_b32_e32 v7, -16, v7
	v_ashrrev_i32_e32 v9, 6, v8
	v_and_b32_e32 v8, 0xc0, v8
	s_and_b32 s21, s0, 3
	v_add_u32_e32 v7, v9, v7
	v_sub_u32_e32 v5, v5, v8
	v_and_b32_e32 v9, 3, v9
	v_lshlrev_b32_e32 v6, 5, v6
	v_ashrrev_i16_sdwa v5, v1, sext(v5) dst_sel:DWORD dst_unused:UNUSED_PAD src0_sel:DWORD src1_sel:BYTE_0
	v_lshlrev_b32_e32 v8, 1, v7
	v_lshrrev_b32_e32 v10, 2, v7
	v_and_or_b32 v9, v7, s1, v9
	s_ashr_i32 s22, s20, 8
	s_lshl_b32 s1, s21, 14
	s_lshl_b32 s0, s0, 10
	s_lshl_b32 s23, s21, 10
	v_readlane_b32 s4, v254, 34
	v_and_b32_e32 v6, 32, v6
	v_bfe_i32 v5, v5, 0, 16
	v_and_b32_e32 v8, 24, v8
	v_and_b32_e32 v10, 4, v10
	v_readlane_b32 s5, v254, 35
	s_add_u32 s4, s15, s4
	v_bfe_u32 v2, v4, 4, 2
	v_or3_b32 v8, v9, v10, v8
	v_add_lshl_u32 v5, v6, v5, 1
	v_and_b32_e32 v4, 15, v4
	s_addc_u32 s5, s16, s5
	s_add_i32 s17, s0, 0
	v_lshl_add_u32 v227, v7, 12, v5
	v_lshl_add_u32 v228, v8, 10, v5
	v_lshlrev_b32_e32 v5, 4, v4
	v_lshlrev_b32_e32 v6, 12, v2
	s_add_i32 s18, s17, 0x10000
	s_mov_b32 s0, m0
	s_mov_b32 m0, s18
	s_nop 0
	global_load_lds_dwordx4 v226, s[4:5]
	s_mov_b32 m0, s0
	v_or3_b32 v229, s1, v6, v5
	v_lshrrev_b32_e32 v232, 8, v229
	v_and_b32_e32 v232, 0xf0, v232
	v_xor_b32_e32 v229, v229, v232
	s_add_i32 s19, s17, 0x12000
	s_mov_b32 s0, m0
	s_mov_b32 m0, s19
	s_nop 0
	global_load_lds_dwordx4 v228, s[4:5]
	s_mov_b32 m0, s0
	v_readlane_b32 s1, v254, 23
	s_mul_i32 s0, s1, s10
	s_add_u32 s6, s13, s0
	s_mul_hi_i32 s0, s1, s10
	s_addc_u32 s7, s14, s0
	s_add_u32 s0, s4, 0x20000
	s_addc_u32 s1, s5, 0
	s_add_i32 s24, s17, 0x14000
	s_mov_b32 s25, m0
	s_mov_b32 m0, s24
	s_nop 0
	global_load_lds_dwordx4 v226, s[0:1]
	s_mov_b32 m0, s25
	s_add_i32 s25, s17, 0x16000
	s_mov_b32 s27, m0
	s_mov_b32 m0, s25
	s_nop 0
	global_load_lds_dwordx4 v228, s[0:1]
	s_mov_b32 m0, s27
	v_readlane_b32 s0, v254, 32
	v_readlane_b32 s1, v254, 33
	s_add_u32 s6, s6, s0
	s_addc_u32 s7, s7, s1
	s_mov_b32 s0, m0
	s_mov_b32 m0, s17
	s_nop 0
	global_load_lds_dwordx4 v225, s[6:7]
	s_mov_b32 m0, s0
	s_add_i32 s28, s17, 0x2000
	s_mov_b32 s0, m0
	s_mov_b32 m0, s28
	s_nop 0
	global_load_lds_dwordx4 v227, s[6:7]
	s_mov_b32 m0, s0
	s_add_u32 s0, s6, 0x100000
	s_addc_u32 s1, s7, 0
	s_add_i32 s29, s23, 0
	s_add_i32 s23, s29, 0x20400
	s_mov_b32 s27, m0
	s_mov_b32 m0, s23
	s_nop 0
	global_load_lds_dwordx4 v229, s[0:1]
	s_mov_b32 m0, s27
	s_add_u32 s0, s6, 0x80000
	s_addc_u32 s1, s7, 0
	s_add_i32 s30, s17, 0x4000
	s_mov_b32 s23, m0
	s_mov_b32 m0, s30
	s_nop 0
	global_load_lds_dwordx4 v225, s[0:1]
	s_mov_b32 m0, s23
	s_add_i32 s31, s17, 0x6000
	s_mov_b32 s23, m0
	s_mov_b32 m0, s31
	s_nop 0
	global_load_lds_dwordx4 v227, s[0:1]
	s_mov_b32 m0, s23
	s_cmp_eq_u32 s22, 1
	s_cselect_b64 s[0:1], -1, 0
	s_cmp_lg_u32 s22, 1
	s_cbranch_scc1 .LBB0_240
	s_barrier
.LBB0_240:
	s_add_u32 s46, s8, 0x35e04000
	v_lshlrev_b32_e32 v5, 3, v2
	v_lshlrev_b32_e32 v2, 4, v2
	v_lshlrev_b32_e32 v7, 2, v4
	s_addc_u32 s47, s9, 0
	v_lshl_or_b32 v6, v4, 6, v2
	s_lshl_b32 s8, s22, 13
	v_and_b32_e32 v7, 32, v7
	v_bitop3_b32 v8, v6, s8, v7 bitop3:0xde
	s_lshl_b32 s8, s21, 12
	v_bitop3_b32 v6, v6, s8, v7 bitop3:0xde
	s_add_u32 s8, s4, 0x80
	s_waitcnt vmcnt(2)
	s_barrier
	s_addc_u32 s9, s5, 0
	s_add_i32 s36, s17, 0x18000
	s_mov_b32 s23, m0
	s_mov_b32 m0, s36
	s_nop 0
	global_load_lds_dwordx4 v226, s[8:9]
	s_mov_b32 m0, s23
	s_add_i32 s37, s17, 0x1a000
	s_mov_b32 s23, m0
	s_mov_b32 m0, s37
	s_nop 0
	global_load_lds_dwordx4 v228, s[8:9]
	s_mov_b32 m0, s23
	s_add_u32 s8, s6, 0x80
	s_addc_u32 s9, s7, 0
	s_add_i32 s51, s17, 0x8000
	s_mov_b32 s23, m0
	s_mov_b32 m0, s51
	s_nop 0
	global_load_lds_dwordx4 v225, s[8:9]
	s_mov_b32 m0, s23
	s_add_i32 s52, s17, 0xa000
	s_mov_b32 s23, m0
	s_mov_b32 m0, s52
	s_nop 0
	global_load_lds_dwordx4 v227, s[8:9]
	s_mov_b32 m0, s23
	s_add_u32 s8, s4, 0x20080
	s_addc_u32 s9, s5, 0
	s_add_i32 s57, s17, 0x1c000
	s_mov_b32 s23, m0
	s_mov_b32 m0, s57
	s_nop 0
	global_load_lds_dwordx4 v226, s[8:9]
	s_mov_b32 m0, s23
	s_add_i32 s58, s17, 0x1e000
	s_add_i32 s59, s17, 0xc000
	s_mov_b32 s23, m0
	s_mov_b32 m0, s58
	s_nop 0
	global_load_lds_dwordx4 v228, s[8:9]
	s_mov_b32 m0, s23
	s_cmpk_lt_u32 s20, 0x100
	s_waitcnt vmcnt(6)
	s_cselect_b64 s[74:75], -1, 0
	s_cmpk_gt_u32 s20, 0xff
	v_lshl_or_b32 v231, s21, 5, v5
	v_lshl_add_u32 v5, v4, 8, 0
	s_mov_b32 s8, 0x20400
	s_cselect_b64 s[76:77], -1, 0
	s_lshl_b32 s78, s22, 2
	v_lshl_or_b32 v230, s22, 6, v4
	v_lshlrev_b32_e32 v232, 4, v4
	v_xor_b32_e32 v232, v232, v2
	v_add3_u32 v232, v5, v232, s8
	v_or_b32_e32 v233, 0x100, v4
	s_ashr_i32 s79, s78, 31
	s_add_i32 s83, s17, 0xe000
	s_mov_b32 s88, 0
	v_add_u32_e32 v234, 0, v6
	v_add_u32_e32 v235, 0, v8
	v_readlane_b32 s60, v254, 40
	v_readlane_b32 s61, v254, 23
	s_barrier
	s_branch .LBB0_243

; #define PG8_STAGE(bufoff, gbase, voff) do { _Pragma("unroll") for (int _i = 0; _i < 2; ++_i) glds16_s((voff)[_i], (const void*)(gbase), ldsbase + (unsigned)((bufoff) + _i * 8192) + ldsw); } while (0)
; #define PG8_STAGEX(pb, gbase) glds16_s(voffX, (const void*)(gbase), ldsbase + (unsigned)(XOFF + (pb) * 4096) + ldsx)
; #define PG8_LDA(dst, b, h) do { _Pragma("unroll") for (int m = 0; m < 4; ++m) _Pragma("unroll") for (int k = 0; k < 2; ++k) dst[m][k] = *(const PG8_LAS bf16x8*)(lds + PG8_SA(b, h) + aoff + m * 2048 + k * 1024); } while (0)
; #define PG8_LDB(dst, b, h) do { _Pragma("unroll") for (int n = 0; n < 2; ++n) _Pragma("unroll") for (int k = 0; k < 2; ++k) dst[n][k] = *(const PG8_LAS bf16x8*)(lds + PG8_SB(b, h) + boff + n * 2048 + k * 1024); } while (0)
; #define PG8_LDX(pb, tp) do { _Pragma("unroll") for (int k = 0; k < 2; ++k) Ax[k] = *(const PG8_LAS bf16x8*)(lds + xoff + (pb) * 4096 + (tp) * 128 + k * 64); } while (0)
; #define PG8_SCHED __builtin_amdgcn_sched_barrier(0)
; template <class Epi, class Sched, bool HM = false>
; __device__ __forceinline__ void gemm_phase(PG8_LAS unsigned char* lds, const Gemm g, const Sched& S, const Epi& E) {
;     ...
;             const char* a1 = cA + (size_t)(t + 1) * kstep;
;             const char* a2 = last ? nA : cA + (size_t)(t + 2) * kstep; const char* b2 = last ? nB : cB + (size_t)(t + 2) * kstep;
;             const char* a3 = a2 + kstep; const char* b3 = b2 + kstep;
;             asm volatile("; uniform bases" : "+s"(a1), "+s"(a2), "+s"(a3), "+s"(b2), "+s"(b3));
;             if (last && has_next) S.a_ready(nxt);
;             const int pb = (t >> 1) & 1;
;             PG8_LDB(B0, 0, 0); PG8_LDB(B1, 0, 1); PG8_SCHED; PG8_LDA(At, 0, 0); if (hasx) PG8_LDX(pb, 0); PG8_STAGE(PG8_SA(1, 1), a1 + hstepA, voffA); PG8_STAGEX(pb ^ 1, a2 + xstep);
.LBB0_256:
	s_add_u32 s34, s27, 0xffffff80
	s_addc_u32 s35, s39, -1
	s_cmp_eq_u32 s23, 4
	s_cselect_b32 s92, s84, s27
	s_cselect_b32 s93, s85, s39
	s_cselect_b32 s9, s91, s38
	s_cselect_b32 s8, s90, s95
	s_add_u32 s4, s92, 0x80
	s_addc_u32 s5, s93, 0
	s_add_u32 s6, s8, 0x80
	s_addc_u32 s7, s9, 0
	v_add_u32_e32 v2, 0x10000, v234
	ds_read_b128 v[166:169], v2
	ds_read_b128 v[170:173], v2 offset:1024
	ds_read_b128 v[174:177], v2 offset:2048
	ds_read_b128 v[178:181], v2 offset:3072
	v_add_u32_e32 v2, 0x14000, v234
	ds_read_b128 v[150:153], v2
	ds_read_b128 v[154:157], v2 offset:1024
	ds_read_b128 v[158:161], v2 offset:2048
	s_waitcnt lgkmcnt(7)
	ds_read_b128 v[162:165], v2 offset:3072
	ds_read_b128 v[206:209], v235
	ds_read_b128 v[210:213], v235 offset:1024
	ds_read_b128 v[198:201], v235 offset:2048
	ds_read_b128 v[202:205], v235 offset:3072
	ds_read_b128 v[190:193], v235 offset:4096
	ds_read_b128 v[194:197], v235 offset:5120
	ds_read_b128 v[182:185], v235 offset:6144
	ds_read_b128 v[186:189], v235 offset:7168
	s_and_b32 s20, s22, 0x1000
	v_cndmask_b32_e64 v2, 0, 1, s[62:63]
	v_cmp_ne_u32_e64 s[42:43], 1, v2
	s_andn2_b64 vcc, exec, s[62:63]
	v_add_u32_e32 v2, s20, v232
	s_cbranch_vccnz .LBB0_258
	ds_read_b128 v[6:9], v2
	v_xor_b32_e32 v10, 64, v2
	ds_read_b128 v[10:13], v10

; #define PG8_STAGE(bufoff, gbase, voff) do { _Pragma("unroll") for (int _i = 0; _i < 2; ++_i) glds16_s((voff)[_i], (const void*)(gbase), ldsbase + (unsigned)((bufoff) + _i * 8192) + ldsw); } while (0)
; #define PG8_LDA(dst, b, h) do { _Pragma("unroll") for (int m = 0; m < 4; ++m) _Pragma("unroll") for (int k = 0; k < 2; ++k) dst[m][k] = *(const PG8_LAS bf16x8*)(lds + PG8_SA(b, h) + aoff + m * 2048 + k * 1024); } while (0)
; #define PG8_LDB(dst, b, h) do { _Pragma("unroll") for (int n = 0; n < 2; ++n) _Pragma("unroll") for (int k = 0; k < 2; ++k) dst[n][k] = *(const PG8_LAS bf16x8*)(lds + PG8_SB(b, h) + boff + n * 2048 + k * 1024); } while (0)
; #define PG8_LDX(pb, tp) do { _Pragma("unroll") for (int k = 0; k < 2; ++k) Ax[k] = *(const PG8_LAS bf16x8*)(lds + xoff + (pb) * 4096 + (tp) * 128 + k * 64); } while (0)
; #define PG8_MMA(ai, bj, At, Bt) do { __builtin_amdgcn_s_setprio(1); _Pragma("unroll") for (int m = 0; m < 4; ++m) _Pragma("unroll") for (int n = 0; n < 2; ++n) _Pragma("unroll") for (int k = 0; k < 2; ++k) \
;         acc[ai][bj][m][n] = __builtin_amdgcn_mfma_f32_16x16x32_bf16(Bt[n][k], At[m][k], acc[ai][bj][m][n], 0, 0, 0); __builtin_amdgcn_s_setprio(0); } while (0)
; #define PG8_WAIT_V(n) asm volatile("s_waitcnt vmcnt(" #n ")" ::: "memory")
; #define PG8_WAIT_L(n) asm volatile("s_waitcnt lgkmcnt(" #n ")" ::: "memory")
; #define PG8_BAR __builtin_amdgcn_s_barrier()
; #define PG8_SCHED __builtin_amdgcn_sched_barrier(0)
; template <class Epi, class Sched, bool HM = false>
; __device__ __forceinline__ void gemm_phase(PG8_LAS unsigned char* lds, const Gemm g, const Sched& S, const Epi& E) {
;     ...
;             PG8_WAIT_V(9); PG8_WAIT_L(0); PG8_BAR; PG8_MMA(0, 0, At, B0); PG8_MMA(0, 1, At, B1); if (hasx) PG8_MMAX(); PG8_BAR; PG8_SCHED;
;             if (!HM) PG8_LDA(At, 0, 1); PG8_STAGE(PG8_SB(0, 0), b2, voffB); PG8_STAGE(PG8_SB(0, 1), b2 + hstepB, voffB); PG8_STAGE(PG8_SA(0, 0), a2, voffA);
;             PG8_WAIT_V(9); PG8_WAIT_L(0); PG8_BAR; if (!HM) { PG8_MMA(1, 0, At, B0); PG8_MMA(1, 1, At, B1); } PG8_BAR; PG8_SCHED;
;             PG8_LDB(B0, 1, 0); PG8_LDB(B1, 1, 1); PG8_SCHED; PG8_LDA(At, 1, 0); if (hasx) PG8_LDX(pb, 1); PG8_STAGE(PG8_SA(0, 1), a2 + hstepA, voffA);
.LBB0_263:
.LBB0_264:
	s_barrier
	ds_read_b128 v[182:185], v235 offset:16384
	ds_read_b128 v[186:189], v235 offset:17408
	ds_read_b128 v[190:193], v235 offset:18432
	ds_read_b128 v[194:197], v235 offset:19456
	ds_read_b128 v[198:201], v235 offset:20480
	ds_read_b128 v[202:205], v235 offset:21504
	ds_read_b128 v[206:209], v235 offset:22528
	ds_read_b128 v[210:213], v235 offset:23552
	s_mov_b32 s20, m0
	s_mov_b32 m0, s18
	s_nop 0
	global_load_lds_dwordx4 v226, s[8:9]
	s_mov_b32 m0, s20
	s_nop 0
	s_mov_b32 s20, m0
	s_mov_b32 m0, s19
	s_nop 0
	global_load_lds_dwordx4 v228, s[8:9]
	s_mov_b32 m0, s20
	s_add_u32 s8, s8, 0x20000
	s_addc_u32 s9, s9, 0
	s_mov_b32 s20, m0
	s_mov_b32 m0, s24
	s_nop 0
	global_load_lds_dwordx4 v226, s[8:9]
	s_mov_b32 m0, s20
	s_nop 0
	s_mov_b32 s20, m0
	s_mov_b32 m0, s25
	s_nop 0
	global_load_lds_dwordx4 v228, s[8:9]
	s_mov_b32 m0, s20
	s_mov_b32 s8, m0
	s_mov_b32 m0, s17
	s_nop 0
	global_load_lds_dwordx4 v225, s[92:93]
	s_mov_b32 m0, s8
	s_nop 0
	s_mov_b32 s8, m0
	s_mov_b32 m0, s28
	s_nop 0
	global_load_lds_dwordx4 v227, s[92:93]
	s_mov_b32 m0, s8
	s_waitcnt vmcnt(9)
	s_waitcnt lgkmcnt(0)
	s_barrier
	s_setprio 1
	s_waitcnt lgkmcnt(7)
	v_mfma_f32_16x16x32_bf16 v[82:85], v[166:169], v[182:185], v[82:85]
	v_mfma_f32_16x16x32_bf16 v[78:81], v[174:177], v[182:185], v[78:81]
	s_waitcnt lgkmcnt(5)
	v_mfma_f32_16x16x32_bf16 v[74:77], v[166:169], v[190:193], v[74:77]
	v_mfma_f32_16x16x32_bf16 v[66:69], v[174:177], v[190:193], v[66:69]
	s_waitcnt lgkmcnt(3)
	v_mfma_f32_16x16x32_bf16 v[58:61], v[166:169], v[198:201], v[58:61]
	v_mfma_f32_16x16x32_bf16 v[50:53], v[174:177], v[198:201], v[50:53]
	s_waitcnt lgkmcnt(1)
	v_mfma_f32_16x16x32_bf16 v[42:45], v[166:169], v[206:209], v[42:45]
	v_mfma_f32_16x16x32_bf16 v[34:37], v[174:177], v[206:209], v[34:37]
	v_mfma_f32_16x16x32_bf16 v[82:85], v[170:173], v[186:189], v[82:85]
	v_mfma_f32_16x16x32_bf16 v[78:81], v[178:181], v[186:189], v[78:81]
	v_mfma_f32_16x16x32_bf16 v[74:77], v[170:173], v[194:197], v[74:77]
	v_mfma_f32_16x16x32_bf16 v[66:69], v[178:181], v[194:197], v[66:69]
	v_mfma_f32_16x16x32_bf16 v[58:61], v[170:173], v[202:205], v[58:61]
	v_mfma_f32_16x16x32_bf16 v[50:53], v[178:181], v[202:205], v[50:53]
	s_waitcnt lgkmcnt(0)
	v_mfma_f32_16x16x32_bf16 v[42:45], v[170:173], v[210:213], v[42:45]
	v_mfma_f32_16x16x32_bf16 v[34:37], v[178:181], v[210:213], v[34:37]
	s_setprio 0
	s_setprio 1
	v_mfma_f32_16x16x32_bf16 v[70:73], v[150:153], v[182:185], v[70:73]
	v_mfma_f32_16x16x32_bf16 v[62:65], v[158:161], v[182:185], v[62:65]
	v_mfma_f32_16x16x32_bf16 v[54:57], v[150:153], v[190:193], v[54:57]
	v_mfma_f32_16x16x32_bf16 v[46:49], v[158:161], v[190:193], v[46:49]
	v_mfma_f32_16x16x32_bf16 v[38:41], v[150:153], v[198:201], v[38:41]
	v_mfma_f32_16x16x32_bf16 v[30:33], v[158:161], v[198:201], v[30:33]
	v_mfma_f32_16x16x32_bf16 v[26:29], v[150:153], v[206:209], v[26:29]
	v_mfma_f32_16x16x32_bf16 v[22:25], v[158:161], v[206:209], v[22:25]
	v_mfma_f32_16x16x32_bf16 v[70:73], v[154:157], v[186:189], v[70:73]
	v_mfma_f32_16x16x32_bf16 v[62:65], v[162:165], v[186:189], v[62:65]
	v_mfma_f32_16x16x32_bf16 v[54:57], v[154:157], v[194:197], v[54:57]
	v_mfma_f32_16x16x32_bf16 v[46:49], v[162:165], v[194:197], v[46:49]
	v_mfma_f32_16x16x32_bf16 v[38:41], v[154:157], v[202:205], v[38:41]
	v_mfma_f32_16x16x32_bf16 v[30:33], v[162:165], v[202:205], v[30:33]
	v_mfma_f32_16x16x32_bf16 v[26:29], v[154:157], v[210:213], v[26:29]
	v_mfma_f32_16x16x32_bf16 v[22:25], v[162:165], v[210:213], v[22:25]
	s_setprio 0
	s_barrier
	v_add_u32_e32 v4, 0x18000, v234
	ds_read_b128 v[166:169], v4
	ds_read_b128 v[170:173], v4 offset:1024
	ds_read_b128 v[174:177], v4 offset:2048
	ds_read_b128 v[178:181], v4 offset:3072
	v_add_u32_e32 v4, 0x1c000, v234
	ds_read_b128 v[150:153], v4
	ds_read_b128 v[154:157], v4 offset:1024
	ds_read_b128 v[158:161], v4 offset:2048
	ds_read_b128 v[162:165], v4 offset:3072
	ds_read_b128 v[206:209], v235 offset:32768
	ds_read_b128 v[210:213], v235 offset:33792
	ds_read_b128 v[198:201], v235 offset:34816
	ds_read_b128 v[202:205], v235 offset:35840
	ds_read_b128 v[190:193], v235 offset:36864
	ds_read_b128 v[194:197], v235 offset:37888
	ds_read_b128 v[182:185], v235 offset:38912
	ds_read_b128 v[186:189], v235 offset:39936
	s_and_b64 vcc, exec, s[42:43]
	s_cbranch_vccnz .LBB0_266
	v_xor_b32_e32 v6, 0x80, v2
	ds_read_b128 v[6:9], v6
	v_xor_b32_e32 v10, 0xc0, v2
	ds_read_b128 v[10:13], v10

; #define PG8_STAGE(bufoff, gbase, voff) do { _Pragma("unroll") for (int _i = 0; _i < 2; ++_i) glds16_s((voff)[_i], (const void*)(gbase), ldsbase + (unsigned)((bufoff) + _i * 8192) + ldsw); } while (0)
; template <class Epi, class Sched, bool HM = false>
; __device__ __forceinline__ void gemm_phase(PG8_LAS unsigned char* lds, const Gemm g, const Sched& S, const Epi& E) {
;     ...
;     for (int i = 0; i < 2; ++i) { int R, C; stage_rc(tid * 16 + i * 8192, R, C); const int Rb = Epi::PERM ? ((R & ~31) + perm32(R & 31)) : R;
;         voffA[i] = (unsigned)(R * g.lda + C) * 2u; voffB[i] = (unsigned)(Rb * g.ldb + C) * 2u; }
;     const unsigned voffX = (unsigned)((4 * (wid & 3) + (lane >> 4)) * g.lda + 8 * (lane & 15)) * 2u;
;     const size_t kstep = (size_t)(BK * 2);
;     const size_t hstepA = (size_t)HALF * g.lda * 2, hstepB = (size_t)HALF * g.ldb * 2;
;     const size_t tstepA = (size_t)(HM ? HALF : g.pms) * g.lda * 2, tstepB = 2 * hstepB, xstep = 2 * hstepA; const bool hasx = g.pms != BM;
;     const unsigned ldsw = (unsigned)wid * 1024u, ldsx = (unsigned)(wid & 3) * 1024u;
;     const unsigned ldsbase = (unsigned)__builtin_amdgcn_readfirstlane((int)(unsigned)(__UINTPTR_TYPE__)lds);
;     const int aoff = lds_byte(wr * 64 + fr, fq * 8), boff = lds_byte(wc * 32 + fr, fq * 8);
;     const int xoff = XOFF + fr * 256 + fq * 16;
;     ...
;     Unit cur, nxt; int ui = 0;
;     if (!S.next(0, cur)) return;
;     f32x4 acc[2][2][4][2]; f32x4 accx[2];
; #pragma unroll
;     for (int a = 0; a < 2; ++a)
; #pragma unroll
;         for (int b = 0; b < 2; ++b)
; #pragma unroll
;             for (int m = 0; m < 4; ++m)
; #pragma unroll
;                 for (int n = 0; n < 2; ++n) acc[a][b][m][n] = (f32x4){0.f, 0.f, 0.f, 0.f};
;     accx[0] = (f32x4){0.f, 0.f, 0.f, 0.f}; accx[1] = accx[0];
;     bf16x8 At[4][2], B0[2][2], B1[2][2], Ax[2];
;     const char* cA = PG8_APTR(cur); const char* cB = PG8_BPTR(cur);
;     S.a_ready(cur);
;     PG8_STAGE(PG8_SB(0, 0), cB, voffB); PG8_STAGE(PG8_SB(0, 1), cB + hstepB, voffB); PG8_STAGE(PG8_SA(0, 0), cA, voffA); PG8_STAGEX(0, cA + xstep); PG8_STAGE(PG8_SA(0, 1), cA + hstepA, voffA);
;     if (wr == 1) PG8_BAR;
;     PG8_WAIT_V(2); PG8_BAR;
;     PG8_STAGE(PG8_SB(1, 0), cB + kstep, voffB); PG8_STAGE(PG8_SA(1, 0), cA + kstep, voffA); PG8_STAGE(PG8_SB(1, 1), cB + hstepB + kstep, voffB);
;     PG8_WAIT_V(6); PG8_BAR;
.LBB0_515:
	s_mov_b64 s[0:1], s[30:31]
	s_mov_b64 s[4:5], s[30:31]
	s_mov_b64 s[8:9], s[30:31]
	s_waitcnt vmcnt(0)
	v_mov_b32_e32 v4, v0
	s_andn2_b64 vcc, exec, s[96:97]
	v_readfirstlane_b32 s20, v4
	s_cbranch_vccnz .LBB0_514
	v_bfe_i32 v7, v4, 27, 1
	v_lshlrev_b32_e32 v5, 4, v4
	v_lshrrev_b32_e32 v7, 22, v7
	v_add_u32_e32 v7, v5, v7
	v_and_b32_e32 v7, 0xfffffc00, v7
	v_sub_u32_e32 v7, v5, v7
	v_ashrrev_i32_e32 v6, 31, v4
	v_lshrrev_b32_e32 v8, 4, v7
	v_lshrrev_b32_e32 v6, 26, v6
	v_bitop3_b32 v7, v8, v7, 32 bitop3:0x6c
	s_add_u32 s14, s0, 0x1a1e4000
	v_add_u32_e32 v6, v4, v6
	v_ashrrev_i32_e32 v9, 31, v7
	s_addc_u32 s15, s1, 0
	v_ashrrev_i32_e32 v6, 6, v6
	v_lshrrev_b32_e32 v9, 26, v9
	s_add_u32 s0, s4, s12
	v_lshlrev_b32_e32 v8, 3, v6
	v_add_u32_e32 v9, v7, v9
	s_addc_u32 s1, s5, 0
	v_and_b32_e32 v8, -16, v8
	v_ashrrev_i32_e32 v10, 6, v9
	v_and_b32_e32 v9, 0xc0, v9
	s_add_u32 s16, s0, 0x42a0000
	v_add_u32_e32 v8, v10, v8
	v_sub_u32_e32 v7, v7, v9
	s_addc_u32 s17, s1, 0
	v_lshlrev_b32_e32 v6, 5, v6
	v_ashrrev_i16_sdwa v7, v1, sext(v7) dst_sel:DWORD dst_unused:UNUSED_PAD src0_sel:DWORD src1_sel:BYTE_0
	v_lshlrev_b32_e32 v9, 1, v8
	v_lshrrev_b32_e32 v11, 2, v8
	v_and_b32_e32 v10, 3, v10
	s_mov_b32 s1, 0xfffe0
	v_and_b32_e32 v6, 32, v6
	v_bfe_i32 v7, v7, 0, 16
	v_and_b32_e32 v9, 24, v9
	v_and_b32_e32 v11, 4, v11
	v_and_or_b32 v10, v8, s1, v10
	v_or3_b32 v9, v10, v11, v9
	v_add_lshl_u32 v6, v6, v7, 1
	v_add_u32_e32 v5, 0x2000, v5
	v_lshl_add_u32 v225, v8, 12, v6
	v_lshl_add_u32 v226, v9, 12, v6
	v_ashrrev_i32_e32 v6, 31, v5
	v_lshrrev_b32_e32 v6, 22, v6
	v_add_u32_e32 v6, v5, v6
	v_ashrrev_i32_e32 v6, 10, v6
	v_mul_i32_i24_e32 v7, 0x400, v6
	v_sub_u32_e32 v5, v5, v7
	v_lshrrev_b32_e32 v7, 4, v5
	v_bitop3_b32 v5, v7, v5, 32 bitop3:0x6c
	v_ashrrev_i32_e32 v8, 31, v5
	v_lshrrev_b32_e32 v8, 26, v8
	v_lshlrev_b32_e32 v7, 3, v6
	v_add_u32_e32 v8, v5, v8
	s_ashr_i32 s0, s20, 6
	v_and_b32_e32 v7, -16, v7
	v_ashrrev_i32_e32 v9, 6, v8
	v_and_b32_e32 v8, 0xc0, v8
	s_and_b32 s21, s0, 3
	v_add_u32_e32 v7, v9, v7
	v_sub_u32_e32 v5, v5, v8
	v_and_b32_e32 v9, 3, v9
	v_lshlrev_b32_e32 v6, 5, v6
	v_ashrrev_i16_sdwa v5, v1, sext(v5) dst_sel:DWORD dst_unused:UNUSED_PAD src0_sel:DWORD src1_sel:BYTE_0
	v_lshlrev_b32_e32 v8, 1, v7
	v_lshrrev_b32_e32 v10, 2, v7
	v_and_or_b32 v9, v7, s1, v9
	s_ashr_i32 s22, s20, 8
	s_lshl_b32 s1, s21, 14
	s_lshl_b32 s0, s0, 10
	s_lshl_b32 s23, s21, 10
	v_readlane_b32 s4, v254, 41
	v_and_b32_e32 v6, 32, v6
	v_bfe_i32 v5, v5, 0, 16
	v_and_b32_e32 v8, 24, v8
	v_and_b32_e32 v10, 4, v10
	v_readlane_b32 s5, v254, 42
	s_add_u32 s4, s16, s4
	v_bfe_u32 v2, v4, 4, 2
	v_or3_b32 v8, v9, v10, v8
	v_add_lshl_u32 v5, v6, v5, 1
	v_and_b32_e32 v4, 15, v4
	s_addc_u32 s5, s17, s5
	s_add_i32 s18, s0, 0
	v_lshl_add_u32 v227, v7, 12, v5
	v_lshl_add_u32 v228, v8, 12, v5
	v_lshlrev_b32_e32 v5, 4, v4
	v_lshlrev_b32_e32 v6, 12, v2
	s_add_i32 s19, s18, 0x10000
	s_mov_b32 s0, m0
	s_mov_b32 m0, s19
	s_nop 0
	global_load_lds_dwordx4 v226, s[4:5]
	s_mov_b32 m0, s0
	v_or3_b32 v229, s1, v6, v5
	v_lshrrev_b32_e32 v232, 8, v229
	v_and_b32_e32 v232, 0xf0, v232
	v_xor_b32_e32 v229, v229, v232
	s_add_i32 s24, s18, 0x12000
	s_mov_b32 s0, m0
	s_mov_b32 m0, s24
	s_nop 0
	global_load_lds_dwordx4 v228, s[4:5]
	s_mov_b32 m0, s0
	v_readlane_b32 s1, v254, 23
	s_mul_i32 s0, s1, s10
	s_add_u32 s6, s14, s0
	s_mul_hi_i32 s0, s1, s10
	s_addc_u32 s7, s15, s0
	s_add_u32 s0, s4, 0x80000
	s_addc_u32 s1, s5, 0
	s_add_i32 s25, s18, 0x14000
	s_mov_b32 s27, m0
	s_mov_b32 m0, s25
	s_nop 0
	global_load_lds_dwordx4 v226, s[0:1]
	s_mov_b32 m0, s27
	s_add_i32 s28, s18, 0x16000
	s_mov_b32 s27, m0
	s_mov_b32 m0, s28
	s_nop 0
	global_load_lds_dwordx4 v228, s[0:1]
	s_mov_b32 m0, s27
	v_readlane_b32 s0, v254, 38
	v_readlane_b32 s1, v254, 39
	s_add_u32 s6, s6, s0
	s_addc_u32 s7, s7, s1
	s_mov_b32 s0, m0
	s_mov_b32 m0, s18
	s_nop 0
	global_load_lds_dwordx4 v225, s[6:7]
	s_mov_b32 m0, s0
	s_add_i32 s29, s18, 0x2000
	s_mov_b32 s0, m0
	s_mov_b32 m0, s29
	s_nop 0
	global_load_lds_dwordx4 v227, s[6:7]
	s_mov_b32 m0, s0
	s_add_u32 s0, s6, 0x100000
	s_addc_u32 s1, s7, 0
	s_add_i32 s30, s23, 0
	s_add_i32 s23, s30, 0x20400
	s_mov_b32 s27, m0
	s_mov_b32 m0, s23
	s_nop 0
	global_load_lds_dwordx4 v229, s[0:1]
	s_mov_b32 m0, s27
	s_add_u32 s0, s6, 0x80000
	s_addc_u32 s1, s7, 0
	s_add_i32 s31, s18, 0x4000
	s_mov_b32 s23, m0
	s_mov_b32 m0, s31
	s_nop 0
	global_load_lds_dwordx4 v225, s[0:1]
	s_mov_b32 m0, s23
	s_add_i32 s36, s18, 0x6000
	s_mov_b32 s23, m0
	s_mov_b32 m0, s36
	s_nop 0
	global_load_lds_dwordx4 v227, s[0:1]
	s_mov_b32 m0, s23
	s_cmp_eq_u32 s22, 1
	s_cselect_b64 s[0:1], -1, 0
	s_cmp_lg_u32 s22, 1
	s_cbranch_scc1 .LBB0_518
	s_barrier
.LBB0_518:
	s_add_u32 s46, s8, 0x2de84000
	v_lshlrev_b32_e32 v5, 3, v2
	v_lshlrev_b32_e32 v2, 4, v2
	v_lshlrev_b32_e32 v7, 2, v4
	s_addc_u32 s47, s9, 0
	v_lshl_or_b32 v6, v4, 6, v2
	s_lshl_b32 s8, s22, 13
	v_and_b32_e32 v7, 32, v7
	v_bitop3_b32 v8, v6, s8, v7 bitop3:0xde
	s_lshl_b32 s8, s21, 12
	v_bitop3_b32 v6, v6, s8, v7 bitop3:0xde
	s_add_u32 s8, s4, 0x80
	s_waitcnt vmcnt(2)
	s_barrier
	s_addc_u32 s9, s5, 0
	s_add_i32 s37, s18, 0x18000
	s_mov_b32 s23, m0
	s_mov_b32 m0, s37
	s_nop 0
	global_load_lds_dwordx4 v226, s[8:9]
	s_mov_b32 m0, s23
	s_add_i32 s51, s18, 0x1a000
	s_mov_b32 s23, m0
	s_mov_b32 m0, s51
	s_nop 0
	global_load_lds_dwordx4 v228, s[8:9]
	s_mov_b32 m0, s23
	s_add_u32 s8, s6, 0x80
	s_addc_u32 s9, s7, 0
	s_add_i32 s52, s18, 0x8000
	s_mov_b32 s23, m0
	s_mov_b32 m0, s52
	s_nop 0
	global_load_lds_dwordx4 v225, s[8:9]
	s_mov_b32 m0, s23
	s_add_i32 s57, s18, 0xa000
	s_mov_b32 s23, m0
	s_mov_b32 m0, s57
	s_nop 0
	global_load_lds_dwordx4 v227, s[8:9]
	s_mov_b32 m0, s23
	s_add_u32 s8, s4, 0x80080
	s_addc_u32 s9, s5, 0
	s_add_i32 s58, s18, 0x1c000
	s_mov_b32 s23, m0
	s_mov_b32 m0, s58
	s_nop 0
	global_load_lds_dwordx4 v226, s[8:9]
	s_mov_b32 m0, s23
	s_add_i32 s59, s18, 0x1e000
	s_add_i32 s83, s18, 0xc000
	s_mov_b32 s23, m0
	s_mov_b32 m0, s59
	s_nop 0
	global_load_lds_dwordx4 v228, s[8:9]
	s_mov_b32 m0, s23
	s_cmpk_lt_u32 s20, 0x100
	s_waitcnt vmcnt(6)
	s_cselect_b64 s[76:77], -1, 0
	s_cmpk_gt_u32 s20, 0xff
	v_lshl_or_b32 v231, s21, 5, v5
	v_lshl_add_u32 v5, v4, 8, 0
	s_mov_b32 s8, 0x20400
	s_cselect_b64 s[78:79], -1, 0
	s_lshl_b32 s84, s22, 2
	v_lshl_or_b32 v230, s22, 6, v4
	v_lshlrev_b32_e32 v232, 4, v4
	v_xor_b32_e32 v232, v232, v2
	v_add3_u32 v232, v5, v232, s8
	v_or_b32_e32 v233, 0x100, v4
	s_ashr_i32 s85, s84, 31
	s_add_i32 s88, s18, 0xe000
	s_mov_b32 s89, 0
	v_add_u32_e32 v234, 0, v6
	v_add_u32_e32 v235, 0, v8
	v_readlane_b32 s60, v254, 40
	v_readlane_b32 s61, v254, 23
	s_barrier
	s_branch .LBB0_521

; #define PG8_STAGE(bufoff, gbase, voff) do { _Pragma("unroll") for (int _i = 0; _i < 2; ++_i) glds16_s((voff)[_i], (const void*)(gbase), ldsbase + (unsigned)((bufoff) + _i * 8192) + ldsw); } while (0)
; #define PG8_STAGEX(pb, gbase) glds16_s(voffX, (const void*)(gbase), ldsbase + (unsigned)(XOFF + (pb) * 4096) + ldsx)
; #define PG8_LDA(dst, b, h) do { _Pragma("unroll") for (int m = 0; m < 4; ++m) _Pragma("unroll") for (int k = 0; k < 2; ++k) dst[m][k] = *(const PG8_LAS bf16x8*)(lds + PG8_SA(b, h) + aoff + m * 2048 + k * 1024); } while (0)
; #define PG8_LDB(dst, b, h) do { _Pragma("unroll") for (int n = 0; n < 2; ++n) _Pragma("unroll") for (int k = 0; k < 2; ++k) dst[n][k] = *(const PG8_LAS bf16x8*)(lds + PG8_SB(b, h) + boff + n * 2048 + k * 1024); } while (0)
; #define PG8_LDX(pb, tp) do { _Pragma("unroll") for (int k = 0; k < 2; ++k) Ax[k] = *(const PG8_LAS bf16x8*)(lds + xoff + (pb) * 4096 + (tp) * 128 + k * 64); } while (0)
; #define PG8_SCHED __builtin_amdgcn_sched_barrier(0)
; template <class Epi, class Sched, bool HM = false>
; __device__ __forceinline__ void gemm_phase(PG8_LAS unsigned char* lds, const Gemm g, const Sched& S, const Epi& E) {
;     ...
;             const char* a1 = cA + (size_t)(t + 1) * kstep;
;             const char* a2 = last ? nA : cA + (size_t)(t + 2) * kstep; const char* b2 = last ? nB : cB + (size_t)(t + 2) * kstep;
;             const char* a3 = a2 + kstep; const char* b3 = b2 + kstep;
;             asm volatile("; uniform bases" : "+s"(a1), "+s"(a2), "+s"(a3), "+s"(b2), "+s"(b3));
;             if (last && has_next) S.a_ready(nxt);
;             const int pb = (t >> 1) & 1;
;             PG8_LDB(B0, 0, 0); PG8_LDB(B1, 0, 1); PG8_SCHED; PG8_LDA(At, 0, 0); if (hasx) PG8_LDX(pb, 0); PG8_STAGE(PG8_SA(1, 1), a1 + hstepA, voffA); PG8_STAGEX(pb ^ 1, a2 + xstep);
.LBB0_534:
	s_add_u32 s34, s27, 0xffffff80
	s_addc_u32 s35, s82, -1
	s_cmp_eq_u32 s23, 28
	s_cselect_b32 s94, s90, s27
	s_cselect_b32 s95, s91, s82
	s_cselect_b32 s9, s93, s39
	s_cselect_b32 s8, s92, s38
	s_add_u32 s4, s94, 0x80
	s_addc_u32 s5, s95, 0
	s_add_u32 s6, s8, 0x80
	s_addc_u32 s7, s9, 0
	v_add_u32_e32 v2, 0x10000, v234
	ds_read_b128 v[166:169], v2
	ds_read_b128 v[170:173], v2 offset:1024
	ds_read_b128 v[174:177], v2 offset:2048
	ds_read_b128 v[178:181], v2 offset:3072
	v_add_u32_e32 v2, 0x14000, v234
	ds_read_b128 v[150:153], v2
	ds_read_b128 v[154:157], v2 offset:1024
	ds_read_b128 v[158:161], v2 offset:2048
	s_waitcnt lgkmcnt(7)
	ds_read_b128 v[162:165], v2 offset:3072
	ds_read_b128 v[206:209], v235
	ds_read_b128 v[210:213], v235 offset:1024
	ds_read_b128 v[198:201], v235 offset:2048
	ds_read_b128 v[202:205], v235 offset:3072
	ds_read_b128 v[190:193], v235 offset:4096
	ds_read_b128 v[194:197], v235 offset:5120
	ds_read_b128 v[182:185], v235 offset:6144
	ds_read_b128 v[186:189], v235 offset:7168
	s_and_b32 s20, s22, 0x1000
	v_cndmask_b32_e64 v2, 0, 1, s[54:55]
	v_cmp_ne_u32_e64 s[42:43], 1, v2
	s_andn2_b64 vcc, exec, s[54:55]
	v_add_u32_e32 v2, s20, v232
	s_cbranch_vccnz .LBB0_536
	ds_read_b128 v[6:9], v2
	v_xor_b32_e32 v10, 64, v2
	ds_read_b128 v[10:13], v10

; #define PG8_STAGE(bufoff, gbase, voff) do { _Pragma("unroll") for (int _i = 0; _i < 2; ++_i) glds16_s((voff)[_i], (const void*)(gbase), ldsbase + (unsigned)((bufoff) + _i * 8192) + ldsw); } while (0)
; #define PG8_LDA(dst, b, h) do { _Pragma("unroll") for (int m = 0; m < 4; ++m) _Pragma("unroll") for (int k = 0; k < 2; ++k) dst[m][k] = *(const PG8_LAS bf16x8*)(lds + PG8_SA(b, h) + aoff + m * 2048 + k * 1024); } while (0)
; #define PG8_LDB(dst, b, h) do { _Pragma("unroll") for (int n = 0; n < 2; ++n) _Pragma("unroll") for (int k = 0; k < 2; ++k) dst[n][k] = *(const PG8_LAS bf16x8*)(lds + PG8_SB(b, h) + boff + n * 2048 + k * 1024); } while (0)
; #define PG8_LDX(pb, tp) do { _Pragma("unroll") for (int k = 0; k < 2; ++k) Ax[k] = *(const PG8_LAS bf16x8*)(lds + xoff + (pb) * 4096 + (tp) * 128 + k * 64); } while (0)
; #define PG8_MMA(ai, bj, At, Bt) do { __builtin_amdgcn_s_setprio(1); _Pragma("unroll") for (int m = 0; m < 4; ++m) _Pragma("unroll") for (int n = 0; n < 2; ++n) _Pragma("unroll") for (int k = 0; k < 2; ++k) \
;         acc[ai][bj][m][n] = __builtin_amdgcn_mfma_f32_16x16x32_bf16(Bt[n][k], At[m][k], acc[ai][bj][m][n], 0, 0, 0); __builtin_amdgcn_s_setprio(0); } while (0)
; #define PG8_WAIT_V(n) asm volatile("s_waitcnt vmcnt(" #n ")" ::: "memory")
; #define PG8_WAIT_L(n) asm volatile("s_waitcnt lgkmcnt(" #n ")" ::: "memory")
; #define PG8_BAR __builtin_amdgcn_s_barrier()
; #define PG8_SCHED __builtin_amdgcn_sched_barrier(0)
; template <class Epi, class Sched, bool HM = false>
; __device__ __forceinline__ void gemm_phase(PG8_LAS unsigned char* lds, const Gemm g, const Sched& S, const Epi& E) {
;     ...
;             PG8_WAIT_V(9); PG8_WAIT_L(0); PG8_BAR; PG8_MMA(0, 0, At, B0); PG8_MMA(0, 1, At, B1); if (hasx) PG8_MMAX(); PG8_BAR; PG8_SCHED;
;             if (!HM) PG8_LDA(At, 0, 1); PG8_STAGE(PG8_SB(0, 0), b2, voffB); PG8_STAGE(PG8_SB(0, 1), b2 + hstepB, voffB); PG8_STAGE(PG8_SA(0, 0), a2, voffA);
;             PG8_WAIT_V(9); PG8_WAIT_L(0); PG8_BAR; if (!HM) { PG8_MMA(1, 0, At, B0); PG8_MMA(1, 1, At, B1); } PG8_BAR; PG8_SCHED;
;             PG8_LDB(B0, 1, 0); PG8_LDB(B1, 1, 1); PG8_SCHED; PG8_LDA(At, 1, 0); if (hasx) PG8_LDX(pb, 1); PG8_STAGE(PG8_SA(0, 1), a2 + hstepA, voffA);
.LBB0_541:
.LBB0_542:
	s_barrier
	ds_read_b128 v[182:185], v235 offset:16384
	ds_read_b128 v[186:189], v235 offset:17408
	ds_read_b128 v[190:193], v235 offset:18432
	ds_read_b128 v[194:197], v235 offset:19456
	ds_read_b128 v[198:201], v235 offset:20480
	ds_read_b128 v[202:205], v235 offset:21504
	ds_read_b128 v[206:209], v235 offset:22528
	ds_read_b128 v[210:213], v235 offset:23552
	s_mov_b32 s20, m0
	s_mov_b32 m0, s19
	s_nop 0
	global_load_lds_dwordx4 v226, s[8:9]
	s_mov_b32 m0, s20
	s_nop 0
	s_mov_b32 s20, m0
	s_mov_b32 m0, s24
	s_nop 0
	global_load_lds_dwordx4 v228, s[8:9]
	s_mov_b32 m0, s20
	s_add_u32 s8, s8, 0x80000
	s_addc_u32 s9, s9, 0
	s_mov_b32 s20, m0
	s_mov_b32 m0, s25
	s_nop 0
	global_load_lds_dwordx4 v226, s[8:9]
	s_mov_b32 m0, s20
	s_nop 0
	s_mov_b32 s20, m0
	s_mov_b32 m0, s28
	s_nop 0
	global_load_lds_dwordx4 v228, s[8:9]
	s_mov_b32 m0, s20
	s_mov_b32 s8, m0
	s_mov_b32 m0, s18
	s_nop 0
	global_load_lds_dwordx4 v225, s[94:95]
	s_mov_b32 m0, s8
	s_nop 0
	s_mov_b32 s8, m0
	s_mov_b32 m0, s29
	s_nop 0
	global_load_lds_dwordx4 v227, s[94:95]
	s_mov_b32 m0, s8
	s_waitcnt vmcnt(9)
	s_waitcnt lgkmcnt(0)
	s_barrier
	s_setprio 1
	s_waitcnt lgkmcnt(7)
	v_mfma_f32_16x16x32_bf16 v[82:85], v[166:169], v[182:185], v[82:85]
	v_mfma_f32_16x16x32_bf16 v[78:81], v[174:177], v[182:185], v[78:81]
	s_waitcnt lgkmcnt(5)
	v_mfma_f32_16x16x32_bf16 v[74:77], v[166:169], v[190:193], v[74:77]
	v_mfma_f32_16x16x32_bf16 v[66:69], v[174:177], v[190:193], v[66:69]
	s_waitcnt lgkmcnt(3)
	v_mfma_f32_16x16x32_bf16 v[58:61], v[166:169], v[198:201], v[58:61]
	v_mfma_f32_16x16x32_bf16 v[50:53], v[174:177], v[198:201], v[50:53]
	s_waitcnt lgkmcnt(1)
	v_mfma_f32_16x16x32_bf16 v[42:45], v[166:169], v[206:209], v[42:45]
	v_mfma_f32_16x16x32_bf16 v[34:37], v[174:177], v[206:209], v[34:37]
	v_mfma_f32_16x16x32_bf16 v[82:85], v[170:173], v[186:189], v[82:85]
	v_mfma_f32_16x16x32_bf16 v[78:81], v[178:181], v[186:189], v[78:81]
	v_mfma_f32_16x16x32_bf16 v[74:77], v[170:173], v[194:197], v[74:77]
	v_mfma_f32_16x16x32_bf16 v[66:69], v[178:181], v[194:197], v[66:69]
	v_mfma_f32_16x16x32_bf16 v[58:61], v[170:173], v[202:205], v[58:61]
	v_mfma_f32_16x16x32_bf16 v[50:53], v[178:181], v[202:205], v[50:53]
	s_waitcnt lgkmcnt(0)
	v_mfma_f32_16x16x32_bf16 v[42:45], v[170:173], v[210:213], v[42:45]
	v_mfma_f32_16x16x32_bf16 v[34:37], v[178:181], v[210:213], v[34:37]
	s_setprio 0
	s_setprio 1
	v_mfma_f32_16x16x32_bf16 v[70:73], v[150:153], v[182:185], v[70:73]
	v_mfma_f32_16x16x32_bf16 v[62:65], v[158:161], v[182:185], v[62:65]
	v_mfma_f32_16x16x32_bf16 v[54:57], v[150:153], v[190:193], v[54:57]
	v_mfma_f32_16x16x32_bf16 v[46:49], v[158:161], v[190:193], v[46:49]
	v_mfma_f32_16x16x32_bf16 v[38:41], v[150:153], v[198:201], v[38:41]
	v_mfma_f32_16x16x32_bf16 v[30:33], v[158:161], v[198:201], v[30:33]
	v_mfma_f32_16x16x32_bf16 v[26:29], v[150:153], v[206:209], v[26:29]
	v_mfma_f32_16x16x32_bf16 v[22:25], v[158:161], v[206:209], v[22:25]
	v_mfma_f32_16x16x32_bf16 v[70:73], v[154:157], v[186:189], v[70:73]
	v_mfma_f32_16x16x32_bf16 v[62:65], v[162:165], v[186:189], v[62:65]
	v_mfma_f32_16x16x32_bf16 v[54:57], v[154:157], v[194:197], v[54:57]
	v_mfma_f32_16x16x32_bf16 v[46:49], v[162:165], v[194:197], v[46:49]
	v_mfma_f32_16x16x32_bf16 v[38:41], v[154:157], v[202:205], v[38:41]
	v_mfma_f32_16x16x32_bf16 v[30:33], v[162:165], v[202:205], v[30:33]
	v_mfma_f32_16x16x32_bf16 v[26:29], v[154:157], v[210:213], v[26:29]
	v_mfma_f32_16x16x32_bf16 v[22:25], v[162:165], v[210:213], v[22:25]
	s_setprio 0
	s_barrier
	v_add_u32_e32 v4, 0x18000, v234
	ds_read_b128 v[166:169], v4
	ds_read_b128 v[170:173], v4 offset:1024
	ds_read_b128 v[174:177], v4 offset:2048
	ds_read_b128 v[178:181], v4 offset:3072
	v_add_u32_e32 v4, 0x1c000, v234
	ds_read_b128 v[150:153], v4
	ds_read_b128 v[154:157], v4 offset:1024
	ds_read_b128 v[158:161], v4 offset:2048
	ds_read_b128 v[162:165], v4 offset:3072
	ds_read_b128 v[206:209], v235 offset:32768
	ds_read_b128 v[210:213], v235 offset:33792
	ds_read_b128 v[198:201], v235 offset:34816
	ds_read_b128 v[202:205], v235 offset:35840
	ds_read_b128 v[190:193], v235 offset:36864
	ds_read_b128 v[194:197], v235 offset:37888
	ds_read_b128 v[182:185], v235 offset:38912
	ds_read_b128 v[186:189], v235 offset:39936
	s_and_b64 vcc, exec, s[42:43]
	s_cbranch_vccnz .LBB0_544
	v_xor_b32_e32 v6, 0x80, v2
	ds_read_b128 v[6:9], v6
	v_xor_b32_e32 v10, 0xc0, v2
	ds_read_b128 v[10:13], v10

; #define PG8_STAGE(bufoff, gbase, voff) do { _Pragma("unroll") for (int _i = 0; _i < 2; ++_i) glds16_s((voff)[_i], (const void*)(gbase), ldsbase + (unsigned)((bufoff) + _i * 8192) + ldsw); } while (0)
; template <class Epi, class Sched, bool HM = false>
; __device__ __forceinline__ void gemm_phase(PG8_LAS unsigned char* lds, const Gemm g, const Sched& S, const Epi& E) {
;     ...
;     for (int i = 0; i < 2; ++i) { int R, C; stage_rc(tid * 16 + i * 8192, R, C); const int Rb = Epi::PERM ? ((R & ~31) + perm32(R & 31)) : R;
;         voffA[i] = (unsigned)(R * g.lda + C) * 2u; voffB[i] = (unsigned)(Rb * g.ldb + C) * 2u; }
;     const unsigned voffX = (unsigned)((4 * (wid & 3) + (lane >> 4)) * g.lda + 8 * (lane & 15)) * 2u;
;     const size_t kstep = (size_t)(BK * 2);
;     const size_t hstepA = (size_t)HALF * g.lda * 2, hstepB = (size_t)HALF * g.ldb * 2;
;     const size_t tstepA = (size_t)(HM ? HALF : g.pms) * g.lda * 2, tstepB = 2 * hstepB, xstep = 2 * hstepA; const bool hasx = g.pms != BM;
;     const unsigned ldsw = (unsigned)wid * 1024u, ldsx = (unsigned)(wid & 3) * 1024u;
;     const unsigned ldsbase = (unsigned)__builtin_amdgcn_readfirstlane((int)(unsigned)(__UINTPTR_TYPE__)lds);
;     const int aoff = lds_byte(wr * 64 + fr, fq * 8), boff = lds_byte(wc * 32 + fr, fq * 8);
;     const int xoff = XOFF + fr * 256 + fq * 16;
;     ...
;     Unit cur, nxt; int ui = 0;
;     if (!S.next(0, cur)) return;
;     f32x4 acc[2][2][4][2]; f32x4 accx[2];
; #pragma unroll
;     for (int a = 0; a < 2; ++a)
; #pragma unroll
;         for (int b = 0; b < 2; ++b)
; #pragma unroll
;             for (int m = 0; m < 4; ++m)
; #pragma unroll
;                 for (int n = 0; n < 2; ++n) acc[a][b][m][n] = (f32x4){0.f, 0.f, 0.f, 0.f};
;     accx[0] = (f32x4){0.f, 0.f, 0.f, 0.f}; accx[1] = accx[0];
;     bf16x8 At[4][2], B0[2][2], B1[2][2], Ax[2];
;     const char* cA = PG8_APTR(cur); const char* cB = PG8_BPTR(cur);
;     S.a_ready(cur);
;     PG8_STAGE(PG8_SB(0, 0), cB, voffB); PG8_STAGE(PG8_SB(0, 1), cB + hstepB, voffB); PG8_STAGE(PG8_SA(0, 0), cA, voffA); PG8_STAGEX(0, cA + xstep); PG8_STAGE(PG8_SA(0, 1), cA + hstepA, voffA);
;     if (wr == 1) PG8_BAR;
;     PG8_WAIT_V(2); PG8_BAR;
;     PG8_STAGE(PG8_SB(1, 0), cB + kstep, voffB); PG8_STAGE(PG8_SA(1, 0), cA + kstep, voffA); PG8_STAGE(PG8_SB(1, 1), cB + hstepB + kstep, voffB);
;     PG8_WAIT_V(6); PG8_BAR;
.LBB0_566:
	v_readlane_b32 s12, v254, 5
	s_mov_b64 s[4:5], s[30:31]
	s_mov_b64 s[6:7], s[30:31]
	s_mov_b64 s[38:39], s[30:31]
	s_mov_b64 s[34:35], s[30:31]
	s_mov_b64 s[8:9], s[30:31]
	s_mov_b64 s[0:1], s[30:31]
	s_waitcnt vmcnt(0)
	v_mov_b32_e32 v4, v0
	v_readlane_b32 s13, v254, 6
	s_andn2_b64 vcc, exec, s[12:13]
	v_readfirstlane_b32 s20, v4
	s_cbranch_vccnz .LBB0_616
	v_bfe_i32 v6, v4, 27, 1
	v_lshlrev_b32_e32 v2, 4, v4
	v_lshrrev_b32_e32 v6, 22, v6
	v_add_u32_e32 v6, v2, v6
	v_and_b32_e32 v6, 0xfffffc00, v6
	v_sub_u32_e32 v6, v2, v6
	v_ashrrev_i32_e32 v5, 31, v4
	v_lshrrev_b32_e32 v7, 4, v6
	v_lshrrev_b32_e32 v5, 26, v5
	v_bitop3_b32 v6, v7, v6, 32 bitop3:0x6c
	s_add_u32 s10, s4, 0x1a1e4000
	v_add_u32_e32 v5, v4, v5
	v_ashrrev_i32_e32 v8, 31, v6
	s_addc_u32 s14, s5, 0
	v_ashrrev_i32_e32 v5, 6, v5
	v_lshrrev_b32_e32 v8, 26, v8
	s_add_u32 s4, s6, s66
	v_lshlrev_b32_e32 v7, 3, v5
	v_add_u32_e32 v8, v6, v8
	s_addc_u32 s5, s7, s67
	v_and_b32_e32 v7, -16, v7
	v_ashrrev_i32_e32 v9, 6, v8
	v_and_b32_e32 v8, 0xc0, v8
	s_add_u32 s15, s4, 0xa0000
	v_add_u32_e32 v7, v9, v7
	v_sub_u32_e32 v6, v6, v8
	s_addc_u32 s45, s5, 0
	v_lshlrev_b32_e32 v5, 5, v5
	v_ashrrev_i16_sdwa v6, v1, sext(v6) dst_sel:DWORD dst_unused:UNUSED_PAD src0_sel:DWORD src1_sel:BYTE_0
	v_lshlrev_b32_e32 v8, 1, v7
	v_lshrrev_b32_e32 v10, 2, v7
	v_and_b32_e32 v9, 3, v9
	s_mov_b32 s5, 0xfffe0
	v_and_b32_e32 v5, 32, v5
	v_bfe_i32 v6, v6, 0, 16
	v_and_b32_e32 v8, 24, v8
	v_and_b32_e32 v10, 4, v10
	v_and_or_b32 v9, v7, s5, v9
	v_or3_b32 v8, v9, v10, v8
	v_add_lshl_u32 v5, v5, v6, 1
	v_add_u32_e32 v2, 0x2000, v2
	v_lshl_add_u32 v225, v7, 12, v5
	v_lshl_add_u32 v226, v8, 12, v5
	v_ashrrev_i32_e32 v5, 31, v2
	v_lshrrev_b32_e32 v5, 22, v5
	v_add_u32_e32 v5, v2, v5
	v_ashrrev_i32_e32 v5, 10, v5
	v_mul_i32_i24_e32 v6, 0x400, v5
	v_sub_u32_e32 v2, v2, v6
	v_lshrrev_b32_e32 v6, 4, v2
	v_bitop3_b32 v2, v6, v2, 32 bitop3:0x6c
	v_ashrrev_i32_e32 v7, 31, v2
	v_lshrrev_b32_e32 v7, 26, v7
	v_lshlrev_b32_e32 v6, 3, v5
	v_add_u32_e32 v7, v2, v7
	v_and_b32_e32 v6, -16, v6
	v_ashrrev_i32_e32 v8, 6, v7
	v_and_b32_e32 v7, 0xc0, v7
	v_add_u32_e32 v6, v8, v6
	v_sub_u32_e32 v2, v2, v7
	v_lshlrev_b32_e32 v5, 5, v5
	v_ashrrev_i16_sdwa v2, v1, sext(v2) dst_sel:DWORD dst_unused:UNUSED_PAD src0_sel:DWORD src1_sel:BYTE_0
	v_lshlrev_b32_e32 v7, 1, v6
	v_lshrrev_b32_e32 v9, 2, v6
	v_and_b32_e32 v8, 3, v8
	v_and_b32_e32 v5, 32, v5
	v_bfe_i32 v2, v2, 0, 16
	v_and_b32_e32 v7, 24, v7
	v_and_b32_e32 v9, 4, v9
	v_and_or_b32 v8, v6, s5, v8
	s_ashr_i32 s4, s20, 6
	v_or3_b32 v7, v8, v9, v7
	v_add_lshl_u32 v2, v5, v2, 1
	s_and_b32 s21, s4, 3
	v_lshl_add_u32 v227, v6, 12, v2
	v_lshl_add_u32 v228, v7, 12, v2
	v_and_b32_e32 v2, 15, v4
	v_bfe_u32 v4, v4, 4, 2
	s_lshl_b32 s5, s21, 14
	v_lshlrev_b32_e32 v5, 12, v4
	v_lshlrev_b32_e32 v6, 4, v2
	s_ashr_i32 s22, s20, 8
	v_or3_b32 v229, s5, v5, v6
	v_lshrrev_b32_e32 v232, 8, v229
	v_and_b32_e32 v232, 0xf0, v232
	v_xor_b32_e32 v229, v229, v232
	s_lshl_b32 s6, s4, 10
	s_lshl_b32 s18, s21, 10
	v_readlane_b32 s4, v254, 46
	v_readlane_b32 s5, v254, 47
	s_add_u32 s4, s15, s4
	s_addc_u32 s5, s45, s5
	s_add_i32 s51, s6, 0
	s_add_i32 s83, s51, 0x10000
	s_mov_b32 s6, m0
	s_mov_b32 m0, s83
	s_nop 0
	global_load_lds_dwordx4 v226, s[4:5]
	s_mov_b32 m0, s6
	s_add_i32 s36, s51, 0x12000
	s_mov_b32 s6, m0
	s_mov_b32 m0, s36
	s_nop 0
	global_load_lds_dwordx4 v228, s[4:5]
	s_mov_b32 m0, s6
	v_readlane_b32 s7, v254, 26
	s_mul_i32 s6, s7, s57
	s_add_u32 s12, s10, s6
	s_mul_hi_i32 s6, s7, s57
	s_addc_u32 s13, s14, s6
	s_add_u32 s6, s4, 0x80000
	s_addc_u32 s7, s5, 0
	s_add_i32 s37, s51, 0x14000
	s_mov_b32 s16, m0
	s_mov_b32 m0, s37
	s_nop 0
	global_load_lds_dwordx4 v226, s[6:7]
	s_mov_b32 m0, s16
	s_add_i32 s16, s51, 0x16000
	s_mov_b32 s17, m0
	s_mov_b32 m0, s16
	s_nop 0
	global_load_lds_dwordx4 v228, s[6:7]
	s_mov_b32 m0, s17
	v_readlane_b32 s6, v254, 43
	v_readlane_b32 s7, v254, 44
	s_add_u32 s6, s12, s6
	s_addc_u32 s7, s13, s7
	s_mov_b32 s12, m0
	s_mov_b32 m0, s51
	s_nop 0
	global_load_lds_dwordx4 v225, s[6:7]
	s_mov_b32 m0, s12
	s_add_i32 s17, s51, 0x2000
	s_mov_b32 s12, m0
	s_mov_b32 m0, s17
	s_nop 0
	global_load_lds_dwordx4 v227, s[6:7]
	s_mov_b32 m0, s12
	s_add_u32 s12, s6, 0x100000
	s_addc_u32 s13, s7, 0
	s_add_i32 s18, s18, 0
	s_add_i32 s19, s18, 0x20400
	s_mov_b32 s23, m0
	s_mov_b32 m0, s19
	s_nop 0
	global_load_lds_dwordx4 v229, s[12:13]
	s_mov_b32 m0, s23
	s_add_u32 s12, s6, 0x80000
	s_addc_u32 s13, s7, 0
	s_add_i32 s19, s51, 0x4000
	s_mov_b32 s23, m0
	s_mov_b32 m0, s19
	s_nop 0
	global_load_lds_dwordx4 v225, s[12:13]
	s_mov_b32 m0, s23
	s_add_i32 s28, s51, 0x6000
	s_mov_b32 s23, m0
	s_mov_b32 m0, s28
	s_nop 0
	global_load_lds_dwordx4 v227, s[12:13]
	s_mov_b32 m0, s23
	s_cmp_eq_u32 s22, 1
	s_cselect_b64 s[74:75], -1, 0
	s_cmp_lg_u32 s22, 1
	s_cbranch_scc1 .LBB0_569
	s_barrier
.LBB0_569:
	s_add_u32 s76, s38, 0x1c3e4000
	s_addc_u32 s77, s39, 0
	s_add_u32 s78, s34, 0x1d4e4000
	s_addc_u32 s79, s35, 0
	s_add_u32 s84, s8, 0x1e5e4000
	s_addc_u32 s85, s9, 0
	s_add_u32 s92, s0, 0x207e4000
	v_lshlrev_b32_e32 v5, 3, v4
	v_lshlrev_b32_e32 v4, 4, v4
	v_lshlrev_b32_e32 v7, 2, v2
	s_addc_u32 s93, s1, 0
	v_lshl_or_b32 v6, v2, 6, v4
	s_lshl_b32 s0, s22, 13
	v_and_b32_e32 v7, 32, v7
	v_bitop3_b32 v8, v6, s0, v7 bitop3:0xde
	s_lshl_b32 s0, s21, 12
	v_bitop3_b32 v6, v6, s0, v7 bitop3:0xde
	s_add_u32 s0, s4, 0x80
	s_waitcnt vmcnt(2)
	s_barrier
	s_addc_u32 s1, s5, 0
	s_add_i32 s29, s51, 0x18000
	s_mov_b32 s8, m0
	s_mov_b32 m0, s29
	s_nop 0
	global_load_lds_dwordx4 v226, s[0:1]
	s_mov_b32 m0, s8
	s_add_i32 s30, s51, 0x1a000
	s_mov_b32 s8, m0
	s_mov_b32 m0, s30
	s_nop 0
	global_load_lds_dwordx4 v228, s[0:1]
	s_mov_b32 m0, s8
	s_add_u32 s0, s6, 0x80
	s_addc_u32 s1, s7, 0
	s_add_i32 s31, s51, 0x8000
	s_mov_b32 s8, m0
	s_mov_b32 m0, s31
	s_nop 0
	global_load_lds_dwordx4 v225, s[0:1]
	s_mov_b32 m0, s8
	s_add_i32 s24, s51, 0xa000
	s_mov_b32 s8, m0
	s_mov_b32 m0, s24
	s_nop 0
	global_load_lds_dwordx4 v227, s[0:1]
	s_mov_b32 m0, s8
	s_add_u32 s0, s4, 0x80080
	s_addc_u32 s1, s5, 0
	s_add_i32 s25, s51, 0x1c000
	s_mov_b32 s8, m0
	s_mov_b32 m0, s25
	s_nop 0
	global_load_lds_dwordx4 v226, s[0:1]
	s_mov_b32 m0, s8
	s_add_i32 s12, s51, 0x1e000
	s_add_i32 s13, s51, 0xc000
	s_mov_b32 s8, m0
	s_mov_b32 m0, s12
	s_nop 0
	global_load_lds_dwordx4 v228, s[0:1]
	s_mov_b32 m0, s8
	s_cmpk_lt_u32 s20, 0x100
	s_waitcnt vmcnt(6)
	s_cselect_b64 s[94:95], -1, 0
	s_cmpk_gt_u32 s20, 0xff
	v_lshl_add_u32 v7, v2, 8, 0
	s_mov_b32 s0, 0x20400
	s_cselect_b64 s[96:97], -1, 0
	s_lshl_b32 s90, s22, 2
	v_lshl_or_b32 v230, s22, 6, v2
	v_lshlrev_b32_e32 v231, 4, v2
	v_xor_b32_e32 v231, v231, v4
	v_add3_u32 v231, v7, v231, s0
	v_lshl_or_b32 v232, s21, 5, v5
	v_or_b32_e32 v233, 0x100, v2
	s_ashr_i32 s91, s90, 31
	s_add_i32 s52, s51, 0xe000
	s_mov_b32 s88, 0
	v_add_u32_e32 v234, 0, v6
	v_add_u32_e32 v235, 0, v8
	v_readlane_b32 s89, v254, 45
	v_readlane_b32 s59, v254, 26
	s_barrier
	s_branch .LBB0_572

; #define PG8_STAGE(bufoff, gbase, voff) do { _Pragma("unroll") for (int _i = 0; _i < 2; ++_i) glds16_s((voff)[_i], (const void*)(gbase), ldsbase + (unsigned)((bufoff) + _i * 8192) + ldsw); } while (0)
; #define PG8_STAGEX(pb, gbase) glds16_s(voffX, (const void*)(gbase), ldsbase + (unsigned)(XOFF + (pb) * 4096) + ldsx)
; #define PG8_LDA(dst, b, h) do { _Pragma("unroll") for (int m = 0; m < 4; ++m) _Pragma("unroll") for (int k = 0; k < 2; ++k) dst[m][k] = *(const PG8_LAS bf16x8*)(lds + PG8_SA(b, h) + aoff + m * 2048 + k * 1024); } while (0)
; #define PG8_LDB(dst, b, h) do { _Pragma("unroll") for (int n = 0; n < 2; ++n) _Pragma("unroll") for (int k = 0; k < 2; ++k) dst[n][k] = *(const PG8_LAS bf16x8*)(lds + PG8_SB(b, h) + boff + n * 2048 + k * 1024); } while (0)
; #define PG8_LDX(pb, tp) do { _Pragma("unroll") for (int k = 0; k < 2; ++k) Ax[k] = *(const PG8_LAS bf16x8*)(lds + xoff + (pb) * 4096 + (tp) * 128 + k * 64); } while (0)
; #define PG8_SCHED __builtin_amdgcn_sched_barrier(0)
; template <class Epi, class Sched, bool HM = false>
; __device__ __forceinline__ void gemm_phase(PG8_LAS unsigned char* lds, const Gemm g, const Sched& S, const Epi& E) {
;     ...
;             const char* a1 = cA + (size_t)(t + 1) * kstep;
;             const char* a2 = last ? nA : cA + (size_t)(t + 2) * kstep; const char* b2 = last ? nB : cB + (size_t)(t + 2) * kstep;
;             const char* a3 = a2 + kstep; const char* b3 = b2 + kstep;
;             asm volatile("; uniform bases" : "+s"(a1), "+s"(a2), "+s"(a3), "+s"(b2), "+s"(b3));
;             if (last && has_next) S.a_ready(nxt);
;             const int pb = (t >> 1) & 1;
;             PG8_LDB(B0, 0, 0); PG8_LDB(B1, 0, 1); PG8_SCHED; PG8_LDA(At, 0, 0); if (hasx) PG8_LDX(pb, 0); PG8_STAGE(PG8_SA(1, 1), a1 + hstepA, voffA); PG8_STAGEX(pb ^ 1, a2 + xstep);
.LBB0_581:
	s_add_u32 s42, s82, 0xffffff80
	s_addc_u32 s43, s27, -1
	s_cmp_eq_u32 s23, 28
	s_cselect_b32 s8, s0, s82
	s_cselect_b32 s9, s1, s27
	s_cselect_b32 s35, s47, s44
	s_cselect_b32 s34, s46, s61
	s_add_u32 s4, s8, 0x80
	s_addc_u32 s5, s9, 0
	s_add_u32 s6, s34, 0x80
	s_addc_u32 s7, s35, 0
	v_add_u32_e32 v2, 0x10000, v234
	ds_read_b128 v[166:169], v2
	ds_read_b128 v[170:173], v2 offset:1024
	ds_read_b128 v[174:177], v2 offset:2048
	ds_read_b128 v[178:181], v2 offset:3072
	v_add_u32_e32 v2, 0x14000, v234
	ds_read_b128 v[150:153], v2
	ds_read_b128 v[154:157], v2 offset:1024
	ds_read_b128 v[158:161], v2 offset:2048
	s_waitcnt lgkmcnt(7)
	ds_read_b128 v[162:165], v2 offset:3072
	ds_read_b128 v[206:209], v235
	ds_read_b128 v[210:213], v235 offset:1024
	ds_read_b128 v[198:201], v235 offset:2048
	ds_read_b128 v[202:205], v235 offset:3072
	ds_read_b128 v[190:193], v235 offset:4096
	ds_read_b128 v[194:197], v235 offset:5120
	ds_read_b128 v[182:185], v235 offset:6144
	ds_read_b128 v[186:189], v235 offset:7168
	s_and_b32 s20, s22, 0x1000
	v_cndmask_b32_e64 v2, 0, 1, s[62:63]
	v_cmp_ne_u32_e64 s[40:41], 1, v2
	s_andn2_b64 vcc, exec, s[62:63]
	v_add_u32_e32 v2, s20, v231
	s_cbranch_vccnz .LBB0_583
	ds_read_b128 v[6:9], v2
	v_xor_b32_e32 v10, 64, v2
	ds_read_b128 v[10:13], v10

; #define PG8_STAGE(bufoff, gbase, voff) do { _Pragma("unroll") for (int _i = 0; _i < 2; ++_i) glds16_s((voff)[_i], (const void*)(gbase), ldsbase + (unsigned)((bufoff) + _i * 8192) + ldsw); } while (0)
; #define PG8_LDA(dst, b, h) do { _Pragma("unroll") for (int m = 0; m < 4; ++m) _Pragma("unroll") for (int k = 0; k < 2; ++k) dst[m][k] = *(const PG8_LAS bf16x8*)(lds + PG8_SA(b, h) + aoff + m * 2048 + k * 1024); } while (0)
; #define PG8_LDB(dst, b, h) do { _Pragma("unroll") for (int n = 0; n < 2; ++n) _Pragma("unroll") for (int k = 0; k < 2; ++k) dst[n][k] = *(const PG8_LAS bf16x8*)(lds + PG8_SB(b, h) + boff + n * 2048 + k * 1024); } while (0)
; #define PG8_LDX(pb, tp) do { _Pragma("unroll") for (int k = 0; k < 2; ++k) Ax[k] = *(const PG8_LAS bf16x8*)(lds + xoff + (pb) * 4096 + (tp) * 128 + k * 64); } while (0)
; #define PG8_MMA(ai, bj, At, Bt) do { __builtin_amdgcn_s_setprio(1); _Pragma("unroll") for (int m = 0; m < 4; ++m) _Pragma("unroll") for (int n = 0; n < 2; ++n) _Pragma("unroll") for (int k = 0; k < 2; ++k) \
;         acc[ai][bj][m][n] = __builtin_amdgcn_mfma_f32_16x16x32_bf16(Bt[n][k], At[m][k], acc[ai][bj][m][n], 0, 0, 0); __builtin_amdgcn_s_setprio(0); } while (0)
; #define PG8_WAIT_V(n) asm volatile("s_waitcnt vmcnt(" #n ")" ::: "memory")
; #define PG8_WAIT_L(n) asm volatile("s_waitcnt lgkmcnt(" #n ")" ::: "memory")
; #define PG8_BAR __builtin_amdgcn_s_barrier()
; #define PG8_SCHED __builtin_amdgcn_sched_barrier(0)
; template <class Epi, class Sched, bool HM = false>
; __device__ __forceinline__ void gemm_phase(PG8_LAS unsigned char* lds, const Gemm g, const Sched& S, const Epi& E) {
;     ...
;             PG8_WAIT_V(9); PG8_WAIT_L(0); PG8_BAR; PG8_MMA(0, 0, At, B0); PG8_MMA(0, 1, At, B1); if (hasx) PG8_MMAX(); PG8_BAR; PG8_SCHED;
;             if (!HM) PG8_LDA(At, 0, 1); PG8_STAGE(PG8_SB(0, 0), b2, voffB); PG8_STAGE(PG8_SB(0, 1), b2 + hstepB, voffB); PG8_STAGE(PG8_SA(0, 0), a2, voffA);
;             PG8_WAIT_V(9); PG8_WAIT_L(0); PG8_BAR; if (!HM) { PG8_MMA(1, 0, At, B0); PG8_MMA(1, 1, At, B1); } PG8_BAR; PG8_SCHED;
;             PG8_LDB(B0, 1, 0); PG8_LDB(B1, 1, 1); PG8_SCHED; PG8_LDA(At, 1, 0); if (hasx) PG8_LDX(pb, 1); PG8_STAGE(PG8_SA(0, 1), a2 + hstepA, voffA);
.LBB0_588:
.LBB0_589:
	s_barrier
	ds_read_b128 v[182:185], v235 offset:16384
	ds_read_b128 v[186:189], v235 offset:17408
	ds_read_b128 v[190:193], v235 offset:18432
	ds_read_b128 v[194:197], v235 offset:19456
	ds_read_b128 v[198:201], v235 offset:20480
	ds_read_b128 v[202:205], v235 offset:21504
	ds_read_b128 v[206:209], v235 offset:22528
	ds_read_b128 v[210:213], v235 offset:23552
	s_mov_b32 s20, m0
	s_mov_b32 m0, s83
	s_nop 0
	global_load_lds_dwordx4 v226, s[34:35]
	s_mov_b32 m0, s20
	s_nop 0
	s_mov_b32 s20, m0
	s_mov_b32 m0, s36
	s_nop 0
	global_load_lds_dwordx4 v228, s[34:35]
	s_mov_b32 m0, s20
	s_add_u32 s20, s34, 0x80000
	s_addc_u32 s21, s35, 0
	s_mov_b32 s34, m0
	s_mov_b32 m0, s37
	s_nop 0
	global_load_lds_dwordx4 v226, s[20:21]
	s_mov_b32 m0, s34
	s_nop 0
	s_mov_b32 s34, m0
	s_mov_b32 m0, s16
	s_nop 0
	global_load_lds_dwordx4 v228, s[20:21]
	s_mov_b32 m0, s34
	s_mov_b32 s20, m0
	s_mov_b32 m0, s51
	s_nop 0
	global_load_lds_dwordx4 v225, s[8:9]
	s_mov_b32 m0, s20
	s_nop 0
	s_mov_b32 s20, m0
	s_mov_b32 m0, s17
	s_nop 0
	global_load_lds_dwordx4 v227, s[8:9]
	s_mov_b32 m0, s20
	s_waitcnt vmcnt(9)
	s_waitcnt lgkmcnt(0)
	s_barrier
	s_setprio 1
	s_waitcnt lgkmcnt(7)
	v_mfma_f32_16x16x32_bf16 v[82:85], v[166:169], v[182:185], v[82:85]
	v_mfma_f32_16x16x32_bf16 v[78:81], v[174:177], v[182:185], v[78:81]
	s_waitcnt lgkmcnt(5)
	v_mfma_f32_16x16x32_bf16 v[66:69], v[166:169], v[190:193], v[66:69]
	v_mfma_f32_16x16x32_bf16 v[62:65], v[174:177], v[190:193], v[62:65]
	s_waitcnt lgkmcnt(3)
	v_mfma_f32_16x16x32_bf16 v[50:53], v[166:169], v[198:201], v[50:53]
	v_mfma_f32_16x16x32_bf16 v[46:49], v[174:177], v[198:201], v[46:49]
	s_waitcnt lgkmcnt(1)
	v_mfma_f32_16x16x32_bf16 v[34:37], v[166:169], v[206:209], v[34:37]
	v_mfma_f32_16x16x32_bf16 v[30:33], v[174:177], v[206:209], v[30:33]
	v_mfma_f32_16x16x32_bf16 v[82:85], v[170:173], v[186:189], v[82:85]
	v_mfma_f32_16x16x32_bf16 v[78:81], v[178:181], v[186:189], v[78:81]
	v_mfma_f32_16x16x32_bf16 v[66:69], v[170:173], v[194:197], v[66:69]
	v_mfma_f32_16x16x32_bf16 v[62:65], v[178:181], v[194:197], v[62:65]
	v_mfma_f32_16x16x32_bf16 v[50:53], v[170:173], v[202:205], v[50:53]
	v_mfma_f32_16x16x32_bf16 v[46:49], v[178:181], v[202:205], v[46:49]
	s_waitcnt lgkmcnt(0)
	v_mfma_f32_16x16x32_bf16 v[34:37], v[170:173], v[210:213], v[34:37]
	v_mfma_f32_16x16x32_bf16 v[30:33], v[178:181], v[210:213], v[30:33]
	s_setprio 0
	s_setprio 1
	v_mfma_f32_16x16x32_bf16 v[74:77], v[150:153], v[182:185], v[74:77]
	v_mfma_f32_16x16x32_bf16 v[70:73], v[158:161], v[182:185], v[70:73]
	v_mfma_f32_16x16x32_bf16 v[58:61], v[150:153], v[190:193], v[58:61]
	v_mfma_f32_16x16x32_bf16 v[54:57], v[158:161], v[190:193], v[54:57]
	v_mfma_f32_16x16x32_bf16 v[42:45], v[150:153], v[198:201], v[42:45]
	v_mfma_f32_16x16x32_bf16 v[38:41], v[158:161], v[198:201], v[38:41]
	v_mfma_f32_16x16x32_bf16 v[26:29], v[150:153], v[206:209], v[26:29]
	v_mfma_f32_16x16x32_bf16 v[22:25], v[158:161], v[206:209], v[22:25]
	v_mfma_f32_16x16x32_bf16 v[74:77], v[154:157], v[186:189], v[74:77]
	v_mfma_f32_16x16x32_bf16 v[70:73], v[162:165], v[186:189], v[70:73]
	v_mfma_f32_16x16x32_bf16 v[58:61], v[154:157], v[194:197], v[58:61]
	v_mfma_f32_16x16x32_bf16 v[54:57], v[162:165], v[194:197], v[54:57]
	v_mfma_f32_16x16x32_bf16 v[42:45], v[154:157], v[202:205], v[42:45]
	v_mfma_f32_16x16x32_bf16 v[38:41], v[162:165], v[202:205], v[38:41]
	v_mfma_f32_16x16x32_bf16 v[26:29], v[154:157], v[210:213], v[26:29]
	v_mfma_f32_16x16x32_bf16 v[22:25], v[162:165], v[210:213], v[22:25]
	s_setprio 0
	s_barrier
	v_add_u32_e32 v4, 0x18000, v234
	ds_read_b128 v[166:169], v4
	ds_read_b128 v[170:173], v4 offset:1024
	ds_read_b128 v[174:177], v4 offset:2048
	ds_read_b128 v[178:181], v4 offset:3072
	v_add_u32_e32 v4, 0x1c000, v234
	ds_read_b128 v[150:153], v4
	ds_read_b128 v[154:157], v4 offset:1024
	ds_read_b128 v[158:161], v4 offset:2048
	ds_read_b128 v[162:165], v4 offset:3072
	ds_read_b128 v[206:209], v235 offset:32768
	ds_read_b128 v[210:213], v235 offset:33792
	ds_read_b128 v[198:201], v235 offset:34816
	ds_read_b128 v[202:205], v235 offset:35840
	ds_read_b128 v[190:193], v235 offset:36864
	ds_read_b128 v[194:197], v235 offset:37888
	ds_read_b128 v[182:185], v235 offset:38912
	ds_read_b128 v[186:189], v235 offset:39936
	s_and_b64 vcc, exec, s[40:41]
	s_cbranch_vccnz .LBB0_591
	v_xor_b32_e32 v6, 0x80, v2
	ds_read_b128 v[6:9], v6
	v_xor_b32_e32 v10, 0xc0, v2
	ds_read_b128 v[10:13], v10

; #define PG8_STAGE(bufoff, gbase, voff) do { _Pragma("unroll") for (int _i = 0; _i < 2; ++_i) glds16_s((voff)[_i], (const void*)(gbase), ldsbase + (unsigned)((bufoff) + _i * 8192) + ldsw); } while (0)
; template <class Epi, class Sched, bool HM = false>
; __device__ __forceinline__ void gemm_phase(PG8_LAS unsigned char* lds, const Gemm g, const Sched& S, const Epi& E) {
;     ...
;     for (int i = 0; i < 2; ++i) { int R, C; stage_rc(tid * 16 + i * 8192, R, C); const int Rb = Epi::PERM ? ((R & ~31) + perm32(R & 31)) : R;
;         voffA[i] = (unsigned)(R * g.lda + C) * 2u; voffB[i] = (unsigned)(Rb * g.ldb + C) * 2u; }
;     const unsigned voffX = (unsigned)((4 * (wid & 3) + (lane >> 4)) * g.lda + 8 * (lane & 15)) * 2u;
;     const size_t kstep = (size_t)(BK * 2);
;     const size_t hstepA = (size_t)HALF * g.lda * 2, hstepB = (size_t)HALF * g.ldb * 2;
;     const size_t tstepA = (size_t)(HM ? HALF : g.pms) * g.lda * 2, tstepB = 2 * hstepB, xstep = 2 * hstepA; const bool hasx = g.pms != BM;
;     const unsigned ldsw = (unsigned)wid * 1024u, ldsx = (unsigned)(wid & 3) * 1024u;
;     const unsigned ldsbase = (unsigned)__builtin_amdgcn_readfirstlane((int)(unsigned)(__UINTPTR_TYPE__)lds);
;     const int aoff = lds_byte(wr * 64 + fr, fq * 8), boff = lds_byte(wc * 32 + fr, fq * 8);
;     const int xoff = XOFF + fr * 256 + fq * 16;
;     ...
;     Unit cur, nxt; int ui = 0;
;     if (!S.next(0, cur)) return;
;     f32x4 acc[2][2][4][2]; f32x4 accx[2];
; #pragma unroll
;     for (int a = 0; a < 2; ++a)
; #pragma unroll
;         for (int b = 0; b < 2; ++b)
; #pragma unroll
;             for (int m = 0; m < 4; ++m)
; #pragma unroll
;                 for (int n = 0; n < 2; ++n) acc[a][b][m][n] = (f32x4){0.f, 0.f, 0.f, 0.f};
;     accx[0] = (f32x4){0.f, 0.f, 0.f, 0.f}; accx[1] = accx[0];
;     bf16x8 At[4][2], B0[2][2], B1[2][2], Ax[2];
;     const char* cA = PG8_APTR(cur); const char* cB = PG8_BPTR(cur);
;     S.a_ready(cur);
;     PG8_STAGE(PG8_SB(0, 0), cB, voffB); PG8_STAGE(PG8_SB(0, 1), cB + hstepB, voffB); PG8_STAGE(PG8_SA(0, 0), cA, voffA); PG8_STAGEX(0, cA + xstep); PG8_STAGE(PG8_SA(0, 1), cA + hstepA, voffA);
;     if (wr == 1) PG8_BAR;
;     PG8_WAIT_V(2); PG8_BAR;
;     PG8_STAGE(PG8_SB(1, 0), cB + kstep, voffB); PG8_STAGE(PG8_SA(1, 0), cA + kstep, voffA); PG8_STAGE(PG8_SB(1, 1), cB + hstepB + kstep, voffB);
;     PG8_WAIT_V(6); PG8_BAR;
.LBB0_968:
	s_mov_b64 s[0:1], s[30:31]
	s_mov_b64 s[4:5], s[30:31]
	s_mov_b64 s[8:9], s[30:31]
	v_mov_b32_e32 v4, v0
	s_andn2_b64 vcc, exec, s[96:97]
	v_readfirstlane_b32 s20, v4
	s_cbranch_vccnz .LBB0_967
	v_bfe_i32 v7, v4, 27, 1
	v_lshlrev_b32_e32 v5, 4, v4
	v_lshrrev_b32_e32 v7, 22, v7
	v_add_u32_e32 v7, v5, v7
	v_and_b32_e32 v7, 0xfffffc00, v7
	v_sub_u32_e32 v7, v5, v7
	v_ashrrev_i32_e32 v6, 31, v4
	v_lshrrev_b32_e32 v8, 4, v7
	v_lshrrev_b32_e32 v6, 26, v6
	v_bitop3_b32 v7, v8, v7, 32 bitop3:0x6c
	s_add_u32 s14, s0, 0x1a1e4000
	v_add_u32_e32 v6, v4, v6
	v_ashrrev_i32_e32 v9, 31, v7
	s_addc_u32 s15, s1, 0
	v_ashrrev_i32_e32 v6, 6, v6
	v_lshrrev_b32_e32 v9, 26, v9
	s_add_u32 s0, s4, s12
	v_lshlrev_b32_e32 v8, 3, v6
	v_add_u32_e32 v9, v7, v9
	s_addc_u32 s1, s5, 0
	v_and_b32_e32 v8, -16, v8
	v_ashrrev_i32_e32 v10, 6, v9
	v_and_b32_e32 v9, 0xc0, v9
	s_add_u32 s16, s0, 0x32a0000
	v_add_u32_e32 v8, v10, v8
	v_sub_u32_e32 v7, v7, v9
	s_addc_u32 s17, s1, 0
	v_lshlrev_b32_e32 v6, 5, v6
	v_ashrrev_i16_sdwa v7, v1, sext(v7) dst_sel:DWORD dst_unused:UNUSED_PAD src0_sel:DWORD src1_sel:BYTE_0
	v_lshlrev_b32_e32 v9, 1, v8
	v_lshrrev_b32_e32 v11, 2, v8
	v_and_b32_e32 v10, 3, v10
	s_mov_b32 s1, 0xfffe0
	v_and_b32_e32 v6, 32, v6
	v_bfe_i32 v7, v7, 0, 16
	v_and_b32_e32 v9, 24, v9
	v_and_b32_e32 v11, 4, v11
	v_and_or_b32 v10, v8, s1, v10
	v_or3_b32 v9, v10, v11, v9
	v_add_lshl_u32 v6, v6, v7, 1
	v_add_u32_e32 v5, 0x2000, v5
	v_lshl_add_u32 v225, v8, 12, v6
	v_lshl_add_u32 v226, v9, 12, v6
	v_ashrrev_i32_e32 v6, 31, v5
	v_lshrrev_b32_e32 v6, 22, v6
	v_add_u32_e32 v6, v5, v6
	v_ashrrev_i32_e32 v6, 10, v6
	v_mul_i32_i24_e32 v7, 0x400, v6
	v_sub_u32_e32 v5, v5, v7
	v_lshrrev_b32_e32 v7, 4, v5
	v_bitop3_b32 v5, v7, v5, 32 bitop3:0x6c
	v_ashrrev_i32_e32 v8, 31, v5
	v_lshrrev_b32_e32 v8, 26, v8
	v_lshlrev_b32_e32 v7, 3, v6
	v_add_u32_e32 v8, v5, v8
	s_ashr_i32 s0, s20, 6
	v_and_b32_e32 v7, -16, v7
	v_ashrrev_i32_e32 v9, 6, v8
	v_and_b32_e32 v8, 0xc0, v8
	s_and_b32 s21, s0, 3
	v_add_u32_e32 v7, v9, v7
	v_sub_u32_e32 v5, v5, v8
	v_and_b32_e32 v9, 3, v9
	v_lshlrev_b32_e32 v6, 5, v6
	v_ashrrev_i16_sdwa v5, v1, sext(v5) dst_sel:DWORD dst_unused:UNUSED_PAD src0_sel:DWORD src1_sel:BYTE_0
	v_lshlrev_b32_e32 v8, 1, v7
	v_lshrrev_b32_e32 v10, 2, v7
	v_and_or_b32 v9, v7, s1, v9
	s_ashr_i32 s22, s20, 8
	s_lshl_b32 s1, s21, 14
	s_lshl_b32 s0, s0, 10
	s_lshl_b32 s23, s21, 10
	v_readlane_b32 s4, v254, 41
	v_and_b32_e32 v6, 32, v6
	v_bfe_i32 v5, v5, 0, 16
	v_and_b32_e32 v8, 24, v8
	v_and_b32_e32 v10, 4, v10
	v_readlane_b32 s5, v254, 42
	s_add_u32 s4, s16, s4
	v_bfe_u32 v2, v4, 4, 2
	v_or3_b32 v8, v9, v10, v8
	v_add_lshl_u32 v5, v6, v5, 1
	v_and_b32_e32 v4, 15, v4
	s_addc_u32 s5, s17, s5
	s_add_i32 s18, s0, 0
	v_lshl_add_u32 v227, v7, 12, v5
	v_lshl_add_u32 v228, v8, 12, v5
	v_lshlrev_b32_e32 v5, 4, v4
	v_lshlrev_b32_e32 v6, 12, v2
	s_add_i32 s19, s18, 0x10000
	s_mov_b32 s0, m0
	s_mov_b32 m0, s19
	s_nop 0
	global_load_lds_dwordx4 v226, s[4:5]
	s_mov_b32 m0, s0
	v_or3_b32 v229, s1, v6, v5
	v_lshrrev_b32_e32 v232, 8, v229
	v_and_b32_e32 v232, 0xf0, v232
	v_xor_b32_e32 v229, v229, v232
	s_add_i32 s24, s18, 0x12000
	s_mov_b32 s0, m0
	s_mov_b32 m0, s24
	s_nop 0
	global_load_lds_dwordx4 v228, s[4:5]
	s_mov_b32 m0, s0
	v_readlane_b32 s1, v254, 23
	s_mul_i32 s0, s1, s10
	s_add_u32 s6, s14, s0
	s_mul_hi_i32 s0, s1, s10
	s_addc_u32 s7, s15, s0
	s_add_u32 s0, s4, 0x80000
	s_addc_u32 s1, s5, 0
	s_add_i32 s25, s18, 0x14000
	s_mov_b32 s27, m0
	s_mov_b32 m0, s25
	s_nop 0
	global_load_lds_dwordx4 v226, s[0:1]
	s_mov_b32 m0, s27
	s_add_i32 s28, s18, 0x16000
	s_mov_b32 s27, m0
	s_mov_b32 m0, s28
	s_nop 0
	global_load_lds_dwordx4 v228, s[0:1]
	s_mov_b32 m0, s27
	v_readlane_b32 s0, v254, 38
	v_readlane_b32 s1, v254, 39
	s_add_u32 s6, s6, s0
	s_addc_u32 s7, s7, s1
	s_mov_b32 s0, m0
	s_mov_b32 m0, s18
	s_nop 0
	global_load_lds_dwordx4 v225, s[6:7]
	s_mov_b32 m0, s0
	s_add_i32 s29, s18, 0x2000
	s_mov_b32 s0, m0
	s_mov_b32 m0, s29
	s_nop 0
	global_load_lds_dwordx4 v227, s[6:7]
	s_mov_b32 m0, s0
	s_add_u32 s0, s6, 0x100000
	s_addc_u32 s1, s7, 0
	s_add_i32 s30, s23, 0
	s_add_i32 s23, s30, 0x20400
	s_mov_b32 s27, m0
	s_mov_b32 m0, s23
	s_nop 0
	global_load_lds_dwordx4 v229, s[0:1]
	s_mov_b32 m0, s27
	s_add_u32 s0, s6, 0x80000
	s_addc_u32 s1, s7, 0
	s_add_i32 s31, s18, 0x4000
	s_mov_b32 s23, m0
	s_mov_b32 m0, s31
	s_nop 0
	global_load_lds_dwordx4 v225, s[0:1]
	s_mov_b32 m0, s23
	s_add_i32 s36, s18, 0x6000
	s_mov_b32 s23, m0
	s_mov_b32 m0, s36
	s_nop 0
	global_load_lds_dwordx4 v227, s[0:1]
	s_mov_b32 m0, s23
	s_cmp_eq_u32 s22, 1
	s_cselect_b64 s[0:1], -1, 0
	s_cmp_lg_u32 s22, 1
	s_cbranch_scc1 .LBB0_971
	s_barrier
.LBB0_971:
	s_add_u32 s44, s8, 0x2de84000
	v_lshlrev_b32_e32 v5, 3, v2
	v_lshlrev_b32_e32 v2, 4, v2
	v_lshlrev_b32_e32 v7, 2, v4
	s_addc_u32 s45, s9, 0
	v_lshl_or_b32 v6, v4, 6, v2
	s_lshl_b32 s8, s22, 13
	v_and_b32_e32 v7, 32, v7
	v_bitop3_b32 v8, v6, s8, v7 bitop3:0xde
	s_lshl_b32 s8, s21, 12
	v_bitop3_b32 v6, v6, s8, v7 bitop3:0xde
	s_add_u32 s8, s4, 0x80
	s_waitcnt vmcnt(2)
	s_barrier
	s_addc_u32 s9, s5, 0
	s_add_i32 s37, s18, 0x18000
	s_mov_b32 s23, m0
	s_mov_b32 m0, s37
	s_nop 0
	global_load_lds_dwordx4 v226, s[8:9]
	s_mov_b32 m0, s23
	s_add_i32 s51, s18, 0x1a000
	s_mov_b32 s23, m0
	s_mov_b32 m0, s51
	s_nop 0
	global_load_lds_dwordx4 v228, s[8:9]
	s_mov_b32 m0, s23
	s_add_u32 s8, s6, 0x80
	s_addc_u32 s9, s7, 0
	s_add_i32 s52, s18, 0x8000
	s_mov_b32 s23, m0
	s_mov_b32 m0, s52
	s_nop 0
	global_load_lds_dwordx4 v225, s[8:9]
	s_mov_b32 m0, s23
	s_add_i32 s56, s18, 0xa000
	s_mov_b32 s23, m0
	s_mov_b32 m0, s56
	s_nop 0
	global_load_lds_dwordx4 v227, s[8:9]
	s_mov_b32 m0, s23
	s_add_u32 s8, s4, 0x80080
	s_addc_u32 s9, s5, 0
	s_add_i32 s57, s18, 0x1c000
	s_mov_b32 s23, m0
	s_mov_b32 m0, s57
	s_nop 0
	global_load_lds_dwordx4 v226, s[8:9]
	s_mov_b32 m0, s23
	s_add_i32 s58, s18, 0x1e000
	s_add_i32 s59, s18, 0xc000
	s_mov_b32 s23, m0
	s_mov_b32 m0, s58
	s_nop 0
	global_load_lds_dwordx4 v228, s[8:9]
	s_mov_b32 m0, s23
	s_cmpk_lt_u32 s20, 0x100
	s_waitcnt vmcnt(6)
	s_cselect_b64 s[46:47], -1, 0
	s_cmpk_gt_u32 s20, 0xff
	v_lshl_or_b32 v231, s21, 5, v5
	v_lshl_add_u32 v5, v4, 8, 0
	s_mov_b32 s8, 0x20400
	s_cselect_b64 s[62:63], -1, 0
	s_lshl_b32 s74, s22, 2
	v_lshl_or_b32 v230, s22, 6, v4
	v_lshlrev_b32_e32 v232, 4, v4
	v_xor_b32_e32 v232, v232, v2
	v_add3_u32 v232, v5, v232, s8
	v_or_b32_e32 v233, 0x100, v4
	s_ashr_i32 s75, s74, 31
	s_add_i32 s83, s18, 0xe000
	s_mov_b32 s84, 0
	v_add_u32_e32 v234, 0, v6
	v_add_u32_e32 v235, 0, v8
	v_readlane_b32 s60, v254, 40
	v_readlane_b32 s61, v254, 23
	s_barrier
	s_branch .LBB0_974

; #define PG8_STAGE(bufoff, gbase, voff) do { _Pragma("unroll") for (int _i = 0; _i < 2; ++_i) glds16_s((voff)[_i], (const void*)(gbase), ldsbase + (unsigned)((bufoff) + _i * 8192) + ldsw); } while (0)
; #define PG8_STAGEX(pb, gbase) glds16_s(voffX, (const void*)(gbase), ldsbase + (unsigned)(XOFF + (pb) * 4096) + ldsx)
; #define PG8_LDA(dst, b, h) do { _Pragma("unroll") for (int m = 0; m < 4; ++m) _Pragma("unroll") for (int k = 0; k < 2; ++k) dst[m][k] = *(const PG8_LAS bf16x8*)(lds + PG8_SA(b, h) + aoff + m * 2048 + k * 1024); } while (0)
; #define PG8_LDB(dst, b, h) do { _Pragma("unroll") for (int n = 0; n < 2; ++n) _Pragma("unroll") for (int k = 0; k < 2; ++k) dst[n][k] = *(const PG8_LAS bf16x8*)(lds + PG8_SB(b, h) + boff + n * 2048 + k * 1024); } while (0)
; #define PG8_LDX(pb, tp) do { _Pragma("unroll") for (int k = 0; k < 2; ++k) Ax[k] = *(const PG8_LAS bf16x8*)(lds + xoff + (pb) * 4096 + (tp) * 128 + k * 64); } while (0)
; #define PG8_SCHED __builtin_amdgcn_sched_barrier(0)
; template <class Epi, class Sched, bool HM = false>
; __device__ __forceinline__ void gemm_phase(PG8_LAS unsigned char* lds, const Gemm g, const Sched& S, const Epi& E) {
;     ...
;             const char* a1 = cA + (size_t)(t + 1) * kstep;
;             const char* a2 = last ? nA : cA + (size_t)(t + 2) * kstep; const char* b2 = last ? nB : cB + (size_t)(t + 2) * kstep;
;             const char* a3 = a2 + kstep; const char* b3 = b2 + kstep;
;             asm volatile("; uniform bases" : "+s"(a1), "+s"(a2), "+s"(a3), "+s"(b2), "+s"(b3));
;             if (last && has_next) S.a_ready(nxt);
;             const int pb = (t >> 1) & 1;
;             PG8_LDB(B0, 0, 0); PG8_LDB(B1, 0, 1); PG8_SCHED; PG8_LDA(At, 0, 0); if (hasx) PG8_LDX(pb, 0); PG8_STAGE(PG8_SA(1, 1), a1 + hstepA, voffA); PG8_STAGEX(pb ^ 1, a2 + xstep);
.LBB0_987:
	s_add_u32 s42, s27, 0xffffff80
	s_addc_u32 s43, s82, -1
	s_cmp_eq_u32 s23, 28
	s_cselect_b32 s8, s76, s27
	s_cselect_b32 s9, s77, s82
	s_cselect_b32 s35, s79, s90
	s_cselect_b32 s34, s78, s89
	s_add_u32 s4, s8, 0x80
	s_addc_u32 s5, s9, 0
	s_add_u32 s6, s34, 0x80
	s_addc_u32 s7, s35, 0
	v_add_u32_e32 v2, 0x10000, v234
	ds_read_b128 v[166:169], v2
	ds_read_b128 v[170:173], v2 offset:1024
	ds_read_b128 v[174:177], v2 offset:2048
	ds_read_b128 v[178:181], v2 offset:3072
	v_add_u32_e32 v2, 0x14000, v234
	ds_read_b128 v[150:153], v2
	ds_read_b128 v[154:157], v2 offset:1024
	ds_read_b128 v[158:161], v2 offset:2048
	s_waitcnt lgkmcnt(7)
	ds_read_b128 v[162:165], v2 offset:3072
	ds_read_b128 v[206:209], v235
	ds_read_b128 v[210:213], v235 offset:1024
	ds_read_b128 v[198:201], v235 offset:2048
	ds_read_b128 v[202:205], v235 offset:3072
	ds_read_b128 v[190:193], v235 offset:4096
	ds_read_b128 v[194:197], v235 offset:5120
	ds_read_b128 v[182:185], v235 offset:6144
	ds_read_b128 v[186:189], v235 offset:7168
	s_and_b32 s20, s22, 0x1000
	v_cndmask_b32_e64 v2, 0, 1, s[54:55]
	v_cmp_ne_u32_e64 s[40:41], 1, v2
	s_andn2_b64 vcc, exec, s[54:55]
	v_add_u32_e32 v2, s20, v232
	s_cbranch_vccnz .LBB0_989
	ds_read_b128 v[6:9], v2
	v_xor_b32_e32 v10, 64, v2
	ds_read_b128 v[10:13], v10

; #define PG8_STAGE(bufoff, gbase, voff) do { _Pragma("unroll") for (int _i = 0; _i < 2; ++_i) glds16_s((voff)[_i], (const void*)(gbase), ldsbase + (unsigned)((bufoff) + _i * 8192) + ldsw); } while (0)
; #define PG8_LDA(dst, b, h) do { _Pragma("unroll") for (int m = 0; m < 4; ++m) _Pragma("unroll") for (int k = 0; k < 2; ++k) dst[m][k] = *(const PG8_LAS bf16x8*)(lds + PG8_SA(b, h) + aoff + m * 2048 + k * 1024); } while (0)
; #define PG8_LDB(dst, b, h) do { _Pragma("unroll") for (int n = 0; n < 2; ++n) _Pragma("unroll") for (int k = 0; k < 2; ++k) dst[n][k] = *(const PG8_LAS bf16x8*)(lds + PG8_SB(b, h) + boff + n * 2048 + k * 1024); } while (0)
; #define PG8_LDX(pb, tp) do { _Pragma("unroll") for (int k = 0; k < 2; ++k) Ax[k] = *(const PG8_LAS bf16x8*)(lds + xoff + (pb) * 4096 + (tp) * 128 + k * 64); } while (0)
; #define PG8_MMA(ai, bj, At, Bt) do { __builtin_amdgcn_s_setprio(1); _Pragma("unroll") for (int m = 0; m < 4; ++m) _Pragma("unroll") for (int n = 0; n < 2; ++n) _Pragma("unroll") for (int k = 0; k < 2; ++k) \
;         acc[ai][bj][m][n] = __builtin_amdgcn_mfma_f32_16x16x32_bf16(Bt[n][k], At[m][k], acc[ai][bj][m][n], 0, 0, 0); __builtin_amdgcn_s_setprio(0); } while (0)
; #define PG8_WAIT_V(n) asm volatile("s_waitcnt vmcnt(" #n ")" ::: "memory")
; #define PG8_WAIT_L(n) asm volatile("s_waitcnt lgkmcnt(" #n ")" ::: "memory")
; #define PG8_BAR __builtin_amdgcn_s_barrier()
; #define PG8_SCHED __builtin_amdgcn_sched_barrier(0)
; template <class Epi, class Sched, bool HM = false>
; __device__ __forceinline__ void gemm_phase(PG8_LAS unsigned char* lds, const Gemm g, const Sched& S, const Epi& E) {
;     ...
;             PG8_WAIT_V(9); PG8_WAIT_L(0); PG8_BAR; PG8_MMA(0, 0, At, B0); PG8_MMA(0, 1, At, B1); if (hasx) PG8_MMAX(); PG8_BAR; PG8_SCHED;
;             if (!HM) PG8_LDA(At, 0, 1); PG8_STAGE(PG8_SB(0, 0), b2, voffB); PG8_STAGE(PG8_SB(0, 1), b2 + hstepB, voffB); PG8_STAGE(PG8_SA(0, 0), a2, voffA);
;             PG8_WAIT_V(9); PG8_WAIT_L(0); PG8_BAR; if (!HM) { PG8_MMA(1, 0, At, B0); PG8_MMA(1, 1, At, B1); } PG8_BAR; PG8_SCHED;
;             PG8_LDB(B0, 1, 0); PG8_LDB(B1, 1, 1); PG8_SCHED; PG8_LDA(At, 1, 0); if (hasx) PG8_LDX(pb, 1); PG8_STAGE(PG8_SA(0, 1), a2 + hstepA, voffA);
.LBB0_994:
.LBB0_995:
	s_barrier
	ds_read_b128 v[182:185], v235 offset:16384
	ds_read_b128 v[186:189], v235 offset:17408
	ds_read_b128 v[190:193], v235 offset:18432
	ds_read_b128 v[194:197], v235 offset:19456
	ds_read_b128 v[198:201], v235 offset:20480
	ds_read_b128 v[202:205], v235 offset:21504
	ds_read_b128 v[206:209], v235 offset:22528
	ds_read_b128 v[210:213], v235 offset:23552
	s_mov_b32 s20, m0
	s_mov_b32 m0, s19
	s_nop 0
	global_load_lds_dwordx4 v226, s[34:35]
	s_mov_b32 m0, s20
	s_nop 0
	s_mov_b32 s20, m0
	s_mov_b32 m0, s24
	s_nop 0
	global_load_lds_dwordx4 v228, s[34:35]
	s_mov_b32 m0, s20
	s_add_u32 s20, s34, 0x80000
	s_addc_u32 s21, s35, 0
	s_mov_b32 s34, m0
	s_mov_b32 m0, s25
	s_nop 0
	global_load_lds_dwordx4 v226, s[20:21]
	s_mov_b32 m0, s34
	s_nop 0
	s_mov_b32 s34, m0
	s_mov_b32 m0, s28
	s_nop 0
	global_load_lds_dwordx4 v228, s[20:21]
	s_mov_b32 m0, s34
	s_mov_b32 s20, m0
	s_mov_b32 m0, s18
	s_nop 0
	global_load_lds_dwordx4 v225, s[8:9]
	s_mov_b32 m0, s20
	s_nop 0
	s_mov_b32 s20, m0
	s_mov_b32 m0, s29
	s_nop 0
	global_load_lds_dwordx4 v227, s[8:9]
	s_mov_b32 m0, s20
	s_waitcnt vmcnt(9)
	s_waitcnt lgkmcnt(0)
	s_barrier
	s_setprio 1
	s_waitcnt lgkmcnt(7)
	v_mfma_f32_16x16x32_bf16 v[82:85], v[166:169], v[182:185], v[82:85]
	v_mfma_f32_16x16x32_bf16 v[78:81], v[174:177], v[182:185], v[78:81]
	s_waitcnt lgkmcnt(5)
	v_mfma_f32_16x16x32_bf16 v[74:77], v[166:169], v[190:193], v[74:77]
	v_mfma_f32_16x16x32_bf16 v[66:69], v[174:177], v[190:193], v[66:69]
	s_waitcnt lgkmcnt(3)
	v_mfma_f32_16x16x32_bf16 v[58:61], v[166:169], v[198:201], v[58:61]
	v_mfma_f32_16x16x32_bf16 v[50:53], v[174:177], v[198:201], v[50:53]
	s_waitcnt lgkmcnt(1)
	v_mfma_f32_16x16x32_bf16 v[42:45], v[166:169], v[206:209], v[42:45]
	v_mfma_f32_16x16x32_bf16 v[34:37], v[174:177], v[206:209], v[34:37]
	v_mfma_f32_16x16x32_bf16 v[82:85], v[170:173], v[186:189], v[82:85]
	v_mfma_f32_16x16x32_bf16 v[78:81], v[178:181], v[186:189], v[78:81]
	v_mfma_f32_16x16x32_bf16 v[74:77], v[170:173], v[194:197], v[74:77]
	v_mfma_f32_16x16x32_bf16 v[66:69], v[178:181], v[194:197], v[66:69]
	v_mfma_f32_16x16x32_bf16 v[58:61], v[170:173], v[202:205], v[58:61]
	v_mfma_f32_16x16x32_bf16 v[50:53], v[178:181], v[202:205], v[50:53]
	s_waitcnt lgkmcnt(0)
	v_mfma_f32_16x16x32_bf16 v[42:45], v[170:173], v[210:213], v[42:45]
	v_mfma_f32_16x16x32_bf16 v[34:37], v[178:181], v[210:213], v[34:37]
	s_setprio 0
	s_setprio 1
	v_mfma_f32_16x16x32_bf16 v[70:73], v[150:153], v[182:185], v[70:73]
	v_mfma_f32_16x16x32_bf16 v[62:65], v[158:161], v[182:185], v[62:65]
	v_mfma_f32_16x16x32_bf16 v[54:57], v[150:153], v[190:193], v[54:57]
	v_mfma_f32_16x16x32_bf16 v[46:49], v[158:161], v[190:193], v[46:49]
	v_mfma_f32_16x16x32_bf16 v[38:41], v[150:153], v[198:201], v[38:41]
	v_mfma_f32_16x16x32_bf16 v[30:33], v[158:161], v[198:201], v[30:33]
	v_mfma_f32_16x16x32_bf16 v[26:29], v[150:153], v[206:209], v[26:29]
	v_mfma_f32_16x16x32_bf16 v[22:25], v[158:161], v[206:209], v[22:25]
	v_mfma_f32_16x16x32_bf16 v[70:73], v[154:157], v[186:189], v[70:73]
	v_mfma_f32_16x16x32_bf16 v[62:65], v[162:165], v[186:189], v[62:65]
	v_mfma_f32_16x16x32_bf16 v[54:57], v[154:157], v[194:197], v[54:57]
	v_mfma_f32_16x16x32_bf16 v[46:49], v[162:165], v[194:197], v[46:49]
	v_mfma_f32_16x16x32_bf16 v[38:41], v[154:157], v[202:205], v[38:41]
	v_mfma_f32_16x16x32_bf16 v[30:33], v[162:165], v[202:205], v[30:33]
	v_mfma_f32_16x16x32_bf16 v[26:29], v[154:157], v[210:213], v[26:29]
	v_mfma_f32_16x16x32_bf16 v[22:25], v[162:165], v[210:213], v[22:25]
	s_setprio 0
	s_barrier
	v_add_u32_e32 v4, 0x18000, v234
	ds_read_b128 v[166:169], v4
	ds_read_b128 v[170:173], v4 offset:1024
	ds_read_b128 v[174:177], v4 offset:2048
	ds_read_b128 v[178:181], v4 offset:3072
	v_add_u32_e32 v4, 0x1c000, v234
	ds_read_b128 v[150:153], v4
	ds_read_b128 v[154:157], v4 offset:1024
	ds_read_b128 v[158:161], v4 offset:2048
	ds_read_b128 v[162:165], v4 offset:3072
	ds_read_b128 v[206:209], v235 offset:32768
	ds_read_b128 v[210:213], v235 offset:33792
	ds_read_b128 v[198:201], v235 offset:34816
	ds_read_b128 v[202:205], v235 offset:35840
	ds_read_b128 v[190:193], v235 offset:36864
	ds_read_b128 v[194:197], v235 offset:37888
	ds_read_b128 v[182:185], v235 offset:38912
	ds_read_b128 v[186:189], v235 offset:39936
	s_and_b64 vcc, exec, s[40:41]
	s_cbranch_vccnz .LBB0_997
	v_xor_b32_e32 v6, 0x80, v2
	ds_read_b128 v[6:9], v6
	v_xor_b32_e32 v10, 0xc0, v2
	ds_read_b128 v[10:13], v10

; #define PG8_STAGE(bufoff, gbase, voff) do { _Pragma("unroll") for (int _i = 0; _i < 2; ++_i) glds16_s((voff)[_i], (const void*)(gbase), ldsbase + (unsigned)((bufoff) + _i * 8192) + ldsw); } while (0)
; template <class Epi, class Sched, bool HM = false>
; __device__ __forceinline__ void gemm_phase(PG8_LAS unsigned char* lds, const Gemm g, const Sched& S, const Epi& E) {
;     ...
;     for (int i = 0; i < 2; ++i) { int R, C; stage_rc(tid * 16 + i * 8192, R, C); const int Rb = Epi::PERM ? ((R & ~31) + perm32(R & 31)) : R;
;         voffA[i] = (unsigned)(R * g.lda + C) * 2u; voffB[i] = (unsigned)(Rb * g.ldb + C) * 2u; }
;     const unsigned voffX = (unsigned)((4 * (wid & 3) + (lane >> 4)) * g.lda + 8 * (lane & 15)) * 2u;
;     const size_t kstep = (size_t)(BK * 2);
;     const size_t hstepA = (size_t)HALF * g.lda * 2, hstepB = (size_t)HALF * g.ldb * 2;
;     const size_t tstepA = (size_t)(HM ? HALF : g.pms) * g.lda * 2, tstepB = 2 * hstepB, xstep = 2 * hstepA; const bool hasx = g.pms != BM;
;     const unsigned ldsw = (unsigned)wid * 1024u, ldsx = (unsigned)(wid & 3) * 1024u;
;     const unsigned ldsbase = (unsigned)__builtin_amdgcn_readfirstlane((int)(unsigned)(__UINTPTR_TYPE__)lds);
;     const int aoff = lds_byte(wr * 64 + fr, fq * 8), boff = lds_byte(wc * 32 + fr, fq * 8);
;     const int xoff = XOFF + fr * 256 + fq * 16;
;     ...
;     Unit cur, nxt; int ui = 0;
;     if (!S.next(0, cur)) return;
;     f32x4 acc[2][2][4][2]; f32x4 accx[2];
; #pragma unroll
;     for (int a = 0; a < 2; ++a)
; #pragma unroll
;         for (int b = 0; b < 2; ++b)
; #pragma unroll
;             for (int m = 0; m < 4; ++m)
; #pragma unroll
;                 for (int n = 0; n < 2; ++n) acc[a][b][m][n] = (f32x4){0.f, 0.f, 0.f, 0.f};
;     accx[0] = (f32x4){0.f, 0.f, 0.f, 0.f}; accx[1] = accx[0];
;     bf16x8 At[4][2], B0[2][2], B1[2][2], Ax[2];
;     const char* cA = PG8_APTR(cur); const char* cB = PG8_BPTR(cur);
;     S.a_ready(cur);
;     PG8_STAGE(PG8_SB(0, 0), cB, voffB); PG8_STAGE(PG8_SB(0, 1), cB + hstepB, voffB); PG8_STAGE(PG8_SA(0, 0), cA, voffA); PG8_STAGEX(0, cA + xstep); PG8_STAGE(PG8_SA(0, 1), cA + hstepA, voffA);
;     if (wr == 1) PG8_BAR;
;     PG8_WAIT_V(2); PG8_BAR;
;     PG8_STAGE(PG8_SB(1, 0), cB + kstep, voffB); PG8_STAGE(PG8_SA(1, 0), cA + kstep, voffA); PG8_STAGE(PG8_SB(1, 1), cB + hstepB + kstep, voffB);
;     PG8_WAIT_V(6); PG8_BAR;
.LBB0_1250:
	s_mov_b64 s[4:5], s[30:31]
	s_mov_b64 s[0:1], s[30:31]
	s_mov_b64 s[8:9], s[30:31]
	v_mov_b32_e32 v4, v0
	s_andn2_b64 vcc, exec, s[96:97]
	v_readfirstlane_b32 s20, v4
	s_cbranch_vccnz .LBB0_1249
	v_bfe_i32 v7, v4, 27, 1
	v_lshlrev_b32_e32 v5, 4, v4
	v_lshrrev_b32_e32 v7, 22, v7
	v_add_u32_e32 v7, v5, v7
	v_and_b32_e32 v7, 0xfffffc00, v7
	v_sub_u32_e32 v7, v5, v7
	v_lshrrev_b32_e32 v8, 4, v7
	v_ashrrev_i32_e32 v6, 31, v4
	v_bitop3_b32 v7, v8, v7, 32 bitop3:0x6c
	s_add_u32 s13, s4, 0x30084000
	v_lshrrev_b32_e32 v6, 26, v6
	v_ashrrev_i32_e32 v9, 31, v7
	s_addc_u32 s14, s5, 0
	v_readlane_b32 s5, v255, 17
	v_add_u32_e32 v6, v4, v6
	v_lshrrev_b32_e32 v9, 26, v9
	s_mul_i32 s4, s5, 0x1600000
	v_ashrrev_i32_e32 v6, 6, v6
	v_add_u32_e32 v9, v7, v9
	s_add_u32 s0, s0, s4
	s_mul_hi_u32 s4, s5, 0x1600000
	v_lshlrev_b32_e32 v8, 3, v6
	v_ashrrev_i32_e32 v10, 6, v9
	v_and_b32_e32 v9, 0xc0, v9
	s_addc_u32 s1, s1, s4
	v_and_b32_e32 v8, -16, v8
	v_lshlrev_b32_e32 v6, 5, v6
	v_sub_u32_e32 v7, v7, v9
	s_add_u32 s15, s0, 0x102a0000
	v_add_u32_e32 v8, v10, v8
	v_and_b32_e32 v6, 32, v6
	v_ashrrev_i16_sdwa v7, v1, sext(v7) dst_sel:DWORD dst_unused:UNUSED_PAD src0_sel:DWORD src1_sel:BYTE_0
	s_addc_u32 s16, s1, 0
	v_add_u32_sdwa v6, v6, sext(v7) dst_sel:DWORD dst_unused:UNUSED_PAD src0_sel:DWORD src1_sel:WORD_0
	v_lshlrev_b32_e32 v7, 1, v8
	v_lshrrev_b32_e32 v9, 2, v8
	v_and_b32_e32 v10, 3, v10
	s_mov_b32 s1, 0x7fffe0
	v_and_b32_e32 v7, 24, v7
	v_and_b32_e32 v9, 4, v9
	v_and_or_b32 v10, v8, s1, v10
	v_or3_b32 v7, v10, v9, v7
	s_movk_i32 s4, 0x1600
	v_mul_lo_u32 v8, v8, s4
	v_mul_u32_u24_e32 v7, 0x1600, v7
	v_add_u32_e32 v5, 0x2000, v5
	v_add_lshl_u32 v225, v6, v8, 1
	v_add_lshl_u32 v226, v7, v6, 1
	v_ashrrev_i32_e32 v6, 31, v5
	v_lshrrev_b32_e32 v6, 22, v6
	v_add_u32_e32 v6, v5, v6
	v_ashrrev_i32_e32 v6, 10, v6
	v_mul_i32_i24_e32 v7, 0x400, v6
	v_sub_u32_e32 v5, v5, v7
	v_lshrrev_b32_e32 v7, 4, v5
	v_bitop3_b32 v5, v7, v5, 32 bitop3:0x6c
	v_ashrrev_i32_e32 v8, 31, v5
	v_lshrrev_b32_e32 v8, 26, v8
	v_add_u32_e32 v8, v5, v8
	v_lshlrev_b32_e32 v7, 3, v6
	v_ashrrev_i32_e32 v9, 6, v8
	v_and_b32_e32 v8, 0xc0, v8
	s_ashr_i32 s0, s20, 6
	v_and_b32_e32 v7, -16, v7
	v_lshlrev_b32_e32 v6, 5, v6
	v_sub_u32_e32 v5, v5, v8
	s_and_b32 s21, s0, 3
	v_add_u32_e32 v7, v9, v7
	v_and_b32_e32 v6, 32, v6
	v_ashrrev_i16_sdwa v5, v1, sext(v5) dst_sel:DWORD dst_unused:UNUSED_PAD src0_sel:DWORD src1_sel:BYTE_0
	v_and_b32_e32 v9, 3, v9
	v_add_u32_sdwa v5, v6, sext(v5) dst_sel:DWORD dst_unused:UNUSED_PAD src0_sel:DWORD src1_sel:WORD_0
	v_lshlrev_b32_e32 v6, 1, v7
	v_lshrrev_b32_e32 v8, 2, v7
	v_and_or_b32 v9, v7, s1, v9
	s_ashr_i32 s22, s20, 8
	s_lshl_b32 s0, s0, 10
	s_lshl_b32 s23, s21, 10
	v_readlane_b32 s1, v254, 50
	v_and_b32_e32 v6, 24, v6
	v_and_b32_e32 v8, 4, v8
	v_mul_lo_u32 v7, v7, s4
	s_add_u32 s4, s15, s1
	v_readlane_b32 s1, v254, 51
	v_or3_b32 v6, v9, v8, v6
	s_addc_u32 s5, s16, s1
	s_add_i32 s17, s0, 0
	v_mul_u32_u24_e32 v6, 0x1600, v6
	s_add_i32 s18, s17, 0x10000
	s_mov_b32 s0, m0
	s_mov_b32 m0, s18
	s_nop 0
	global_load_lds_dwordx4 v226, s[4:5]
	s_mov_b32 m0, s0
	v_add_lshl_u32 v228, v6, v5, 1
	s_add_i32 s19, s17, 0x12000
	s_mov_b32 s0, m0
	s_mov_b32 m0, s19
	s_nop 0
	global_load_lds_dwordx4 v228, s[4:5]
	s_mov_b32 m0, s0
	v_readlane_b32 s1, v254, 23
	s_mul_i32 s0, s1, s10
	s_add_u32 s6, s13, s0
	s_mul_hi_i32 s0, s1, s10
	s_addc_u32 s7, s14, s0
	s_add_u32 s0, s4, 0x160000
	s_addc_u32 s1, s5, 0
	s_add_i32 s24, s17, 0x14000
	s_mov_b32 s25, m0
	s_mov_b32 m0, s24
	s_nop 0
	global_load_lds_dwordx4 v226, s[0:1]
	s_mov_b32 m0, s25
	s_add_i32 s25, s17, 0x16000
	s_mov_b32 s27, m0
	s_mov_b32 m0, s25
	s_nop 0
	global_load_lds_dwordx4 v228, s[0:1]
	s_mov_b32 m0, s27
	v_readlane_b32 s0, v254, 37
	s_add_u32 s6, s6, s0
	v_readlane_b32 s0, v254, 36
	s_addc_u32 s7, s7, s0
	s_mov_b32 s0, m0
	s_mov_b32 m0, s17
	s_nop 0
	global_load_lds_dwordx4 v225, s[6:7]
	s_mov_b32 m0, s0
	v_add_lshl_u32 v227, v5, v7, 1
	s_add_i32 s28, s17, 0x2000
	s_mov_b32 s0, m0
	s_mov_b32 m0, s28
	s_nop 0
	global_load_lds_dwordx4 v227, s[6:7]
	s_mov_b32 m0, s0
	v_bfe_u32 v2, v4, 4, 2
	s_add_u32 s0, s6, 0x2c0000
	v_lshl_or_b32 v5, s21, 2, v2
	v_lshlrev_b32_e32 v232, 4, v5
	s_addc_u32 s1, s7, 0
	s_add_i32 s29, s23, 0
	v_and_b32_e32 v4, 15, v4
	v_mul_u32_u24_e32 v5, 0x2c00, v5
	s_add_i32 s23, s29, 0x20400
	v_lshl_or_b32 v229, v4, 4, v5
	v_xor_b32_e32 v229, v229, v232
	s_mov_b32 s27, m0
	s_mov_b32 m0, s23
	s_nop 0
	global_load_lds_dwordx4 v229, s[0:1]
	s_mov_b32 m0, s27
	s_add_u32 s0, s6, 0x160000
	s_addc_u32 s1, s7, 0
	s_add_i32 s30, s17, 0x4000
	s_mov_b32 s23, m0
	s_mov_b32 m0, s30
	s_nop 0
	global_load_lds_dwordx4 v225, s[0:1]
	s_mov_b32 m0, s23
	s_add_i32 s31, s17, 0x6000
	s_mov_b32 s23, m0
	s_mov_b32 m0, s31
	s_nop 0
	global_load_lds_dwordx4 v227, s[0:1]
	s_mov_b32 m0, s23
	s_cmp_eq_u32 s22, 1
	s_cselect_b64 s[0:1], -1, 0
	s_cmp_lg_u32 s22, 1
	s_cbranch_scc1 .LBB0_1253
	s_barrier
.LBB0_1253:
	s_add_u32 s42, s8, 0x2de84000
	v_lshlrev_b32_e32 v5, 3, v2
	v_lshlrev_b32_e32 v2, 4, v2
	v_lshlrev_b32_e32 v7, 2, v4
	s_addc_u32 s43, s9, 0
	v_lshl_or_b32 v6, v4, 6, v2
	s_lshl_b32 s8, s22, 13
	v_and_b32_e32 v7, 32, v7
	v_bitop3_b32 v8, v6, s8, v7 bitop3:0xde
	s_lshl_b32 s8, s21, 12
	v_bitop3_b32 v6, v6, s8, v7 bitop3:0xde
	s_add_u32 s8, s4, 0x80
	s_waitcnt vmcnt(2)
	s_barrier
	s_addc_u32 s9, s5, 0
	s_add_i32 s51, s17, 0x18000
	s_mov_b32 s23, m0
	s_mov_b32 m0, s51
	s_nop 0
	global_load_lds_dwordx4 v226, s[8:9]
	s_mov_b32 m0, s23
	s_add_i32 s52, s17, 0x1a000
	s_mov_b32 s23, m0
	s_mov_b32 m0, s52
	s_nop 0
	global_load_lds_dwordx4 v228, s[8:9]
	s_mov_b32 m0, s23
	s_add_u32 s8, s6, 0x80
	s_addc_u32 s9, s7, 0
	s_add_i32 s62, s17, 0x8000
	s_mov_b32 s23, m0
	s_mov_b32 m0, s62
	s_nop 0
	global_load_lds_dwordx4 v225, s[8:9]
	s_mov_b32 m0, s23
	s_add_i32 s63, s17, 0xa000
	s_mov_b32 s23, m0
	s_mov_b32 m0, s63
	s_nop 0
	global_load_lds_dwordx4 v227, s[8:9]
	s_mov_b32 m0, s23
	s_add_u32 s8, s4, 0x160080
	s_addc_u32 s9, s5, 0
	s_add_i32 s74, s17, 0x1c000
	s_mov_b32 s23, m0
	s_mov_b32 m0, s74
	s_nop 0
	global_load_lds_dwordx4 v226, s[8:9]
	s_mov_b32 m0, s23
	s_add_i32 s75, s17, 0x1e000
	s_add_i32 s76, s17, 0xc000
	s_mov_b32 s23, m0
	s_mov_b32 m0, s75
	s_nop 0
	global_load_lds_dwordx4 v228, s[8:9]
	s_mov_b32 m0, s23
	s_cmpk_lt_u32 s20, 0x100
	s_waitcnt vmcnt(6)
	s_cselect_b64 s[44:45], -1, 0
	s_cmpk_gt_u32 s20, 0xff
	v_lshl_or_b32 v231, s21, 5, v5
	v_lshl_add_u32 v5, v4, 8, 0
	s_mov_b32 s8, 0x20400
	s_cselect_b64 s[46:47], -1, 0
	s_lshl_b32 s56, s22, 2
	v_lshl_or_b32 v230, s22, 6, v4
	v_lshlrev_b32_e32 v232, 4, v4
	v_xor_b32_e32 v232, v232, v2
	v_add3_u32 v232, v5, v232, s8
	v_or_b32_e32 v233, 0x100, v4
	s_ashr_i32 s57, s56, 31
	s_add_i32 s77, s17, 0xe000
	s_mov_b32 s78, 0
	v_add_u32_e32 v234, 0, v6
	v_add_u32_e32 v235, 0, v8
	v_readlane_b32 s84, v254, 40
	v_readlane_b32 s85, v254, 23
	s_barrier
	s_branch .LBB0_1256

; #define PG8_STAGE(bufoff, gbase, voff) do { _Pragma("unroll") for (int _i = 0; _i < 2; ++_i) glds16_s((voff)[_i], (const void*)(gbase), ldsbase + (unsigned)((bufoff) + _i * 8192) + ldsw); } while (0)
; #define PG8_STAGEX(pb, gbase) glds16_s(voffX, (const void*)(gbase), ldsbase + (unsigned)(XOFF + (pb) * 4096) + ldsx)
; #define PG8_LDA(dst, b, h) do { _Pragma("unroll") for (int m = 0; m < 4; ++m) _Pragma("unroll") for (int k = 0; k < 2; ++k) dst[m][k] = *(const PG8_LAS bf16x8*)(lds + PG8_SA(b, h) + aoff + m * 2048 + k * 1024); } while (0)
; #define PG8_LDB(dst, b, h) do { _Pragma("unroll") for (int n = 0; n < 2; ++n) _Pragma("unroll") for (int k = 0; k < 2; ++k) dst[n][k] = *(const PG8_LAS bf16x8*)(lds + PG8_SB(b, h) + boff + n * 2048 + k * 1024); } while (0)
; #define PG8_LDX(pb, tp) do { _Pragma("unroll") for (int k = 0; k < 2; ++k) Ax[k] = *(const PG8_LAS bf16x8*)(lds + xoff + (pb) * 4096 + (tp) * 128 + k * 64); } while (0)
; #define PG8_SCHED __builtin_amdgcn_sched_barrier(0)
; template <class Epi, class Sched, bool HM = false>
; __device__ __forceinline__ void gemm_phase(PG8_LAS unsigned char* lds, const Gemm g, const Sched& S, const Epi& E) {
;     ...
;             const char* a1 = cA + (size_t)(t + 1) * kstep;
;             const char* a2 = last ? nA : cA + (size_t)(t + 2) * kstep; const char* b2 = last ? nB : cB + (size_t)(t + 2) * kstep;
;             const char* a3 = a2 + kstep; const char* b3 = b2 + kstep;
;             asm volatile("; uniform bases" : "+s"(a1), "+s"(a2), "+s"(a3), "+s"(b2), "+s"(b3));
;             if (last && has_next) S.a_ready(nxt);
;             const int pb = (t >> 1) & 1;
;             PG8_LDB(B0, 0, 0); PG8_LDB(B1, 0, 1); PG8_SCHED; PG8_LDA(At, 0, 0); if (hasx) PG8_LDX(pb, 0); PG8_STAGE(PG8_SA(1, 1), a1 + hstepA, voffA); PG8_STAGEX(pb ^ 1, a2 + xstep);
.LBB0_1269:
	s_add_u32 s40, s27, 0xffffff80
	s_addc_u32 s41, s82, -1
	s_cmpk_eq_i32 s23, 0x54
	s_cselect_b32 s8, s58, s27
	s_cselect_b32 s9, s59, s82
	s_cselect_b32 s35, s61, s89
	s_cselect_b32 s34, s60, s88
	s_add_u32 s4, s8, 0x80
	s_addc_u32 s5, s9, 0
	s_add_u32 s6, s34, 0x80
	s_addc_u32 s7, s35, 0
	v_add_u32_e32 v2, 0x10000, v234
	ds_read_b128 v[166:169], v2
	ds_read_b128 v[170:173], v2 offset:1024
	ds_read_b128 v[174:177], v2 offset:2048
	ds_read_b128 v[178:181], v2 offset:3072
	v_add_u32_e32 v2, 0x14000, v234
	ds_read_b128 v[150:153], v2
	ds_read_b128 v[154:157], v2 offset:1024
	ds_read_b128 v[158:161], v2 offset:2048
	s_waitcnt lgkmcnt(7)
	ds_read_b128 v[162:165], v2 offset:3072
	ds_read_b128 v[206:209], v235
	ds_read_b128 v[210:213], v235 offset:1024
	ds_read_b128 v[198:201], v235 offset:2048
	ds_read_b128 v[202:205], v235 offset:3072
	ds_read_b128 v[190:193], v235 offset:4096
	ds_read_b128 v[194:197], v235 offset:5120
	ds_read_b128 v[182:185], v235 offset:6144
	ds_read_b128 v[186:189], v235 offset:7168
	s_and_b32 s20, s22, 0x1000
	v_cndmask_b32_e64 v2, 0, 1, s[54:55]
	v_cmp_ne_u32_e64 s[38:39], 1, v2
	s_andn2_b64 vcc, exec, s[54:55]
	v_add_u32_e32 v2, s20, v232
	s_cbranch_vccnz .LBB0_1271
	ds_read_b128 v[6:9], v2
	v_xor_b32_e32 v10, 64, v2
	ds_read_b128 v[10:13], v10

; #define PG8_STAGE(bufoff, gbase, voff) do { _Pragma("unroll") for (int _i = 0; _i < 2; ++_i) glds16_s((voff)[_i], (const void*)(gbase), ldsbase + (unsigned)((bufoff) + _i * 8192) + ldsw); } while (0)
; #define PG8_LDA(dst, b, h) do { _Pragma("unroll") for (int m = 0; m < 4; ++m) _Pragma("unroll") for (int k = 0; k < 2; ++k) dst[m][k] = *(const PG8_LAS bf16x8*)(lds + PG8_SA(b, h) + aoff + m * 2048 + k * 1024); } while (0)
; #define PG8_LDB(dst, b, h) do { _Pragma("unroll") for (int n = 0; n < 2; ++n) _Pragma("unroll") for (int k = 0; k < 2; ++k) dst[n][k] = *(const PG8_LAS bf16x8*)(lds + PG8_SB(b, h) + boff + n * 2048 + k * 1024); } while (0)
; #define PG8_LDX(pb, tp) do { _Pragma("unroll") for (int k = 0; k < 2; ++k) Ax[k] = *(const PG8_LAS bf16x8*)(lds + xoff + (pb) * 4096 + (tp) * 128 + k * 64); } while (0)
; #define PG8_MMA(ai, bj, At, Bt) do { __builtin_amdgcn_s_setprio(1); _Pragma("unroll") for (int m = 0; m < 4; ++m) _Pragma("unroll") for (int n = 0; n < 2; ++n) _Pragma("unroll") for (int k = 0; k < 2; ++k) \
;         acc[ai][bj][m][n] = __builtin_amdgcn_mfma_f32_16x16x32_bf16(Bt[n][k], At[m][k], acc[ai][bj][m][n], 0, 0, 0); __builtin_amdgcn_s_setprio(0); } while (0)
; #define PG8_WAIT_V(n) asm volatile("s_waitcnt vmcnt(" #n ")" ::: "memory")
; #define PG8_WAIT_L(n) asm volatile("s_waitcnt lgkmcnt(" #n ")" ::: "memory")
; #define PG8_BAR __builtin_amdgcn_s_barrier()
; #define PG8_SCHED __builtin_amdgcn_sched_barrier(0)
; template <class Epi, class Sched, bool HM = false>
; __device__ __forceinline__ void gemm_phase(PG8_LAS unsigned char* lds, const Gemm g, const Sched& S, const Epi& E) {
;     ...
;             PG8_WAIT_V(9); PG8_WAIT_L(0); PG8_BAR; PG8_MMA(0, 0, At, B0); PG8_MMA(0, 1, At, B1); if (hasx) PG8_MMAX(); PG8_BAR; PG8_SCHED;
;             if (!HM) PG8_LDA(At, 0, 1); PG8_STAGE(PG8_SB(0, 0), b2, voffB); PG8_STAGE(PG8_SB(0, 1), b2 + hstepB, voffB); PG8_STAGE(PG8_SA(0, 0), a2, voffA);
;             PG8_WAIT_V(9); PG8_WAIT_L(0); PG8_BAR; if (!HM) { PG8_MMA(1, 0, At, B0); PG8_MMA(1, 1, At, B1); } PG8_BAR; PG8_SCHED;
;             PG8_LDB(B0, 1, 0); PG8_LDB(B1, 1, 1); PG8_SCHED; PG8_LDA(At, 1, 0); if (hasx) PG8_LDX(pb, 1); PG8_STAGE(PG8_SA(0, 1), a2 + hstepA, voffA);
.LBB0_1276:
.LBB0_1277:
	s_barrier
	ds_read_b128 v[182:185], v235 offset:16384
	ds_read_b128 v[186:189], v235 offset:17408
	ds_read_b128 v[190:193], v235 offset:18432
	ds_read_b128 v[194:197], v235 offset:19456
	ds_read_b128 v[198:201], v235 offset:20480
	ds_read_b128 v[202:205], v235 offset:21504
	ds_read_b128 v[206:209], v235 offset:22528
	ds_read_b128 v[210:213], v235 offset:23552
	s_mov_b32 s20, m0
	s_mov_b32 m0, s18
	s_nop 0
	global_load_lds_dwordx4 v226, s[34:35]
	s_mov_b32 m0, s20
	s_nop 0
	s_mov_b32 s20, m0
	s_mov_b32 m0, s19
	s_nop 0
	global_load_lds_dwordx4 v228, s[34:35]
	s_mov_b32 m0, s20
	s_add_u32 s20, s34, 0x160000
	s_addc_u32 s21, s35, 0
	s_mov_b32 s34, m0
	s_mov_b32 m0, s24
	s_nop 0
	global_load_lds_dwordx4 v226, s[20:21]
	s_mov_b32 m0, s34
	s_nop 0
	s_mov_b32 s34, m0
	s_mov_b32 m0, s25
	s_nop 0
	global_load_lds_dwordx4 v228, s[20:21]
	s_mov_b32 m0, s34
	s_mov_b32 s20, m0
	s_mov_b32 m0, s17
	s_nop 0
	global_load_lds_dwordx4 v225, s[8:9]
	s_mov_b32 m0, s20
	s_nop 0
	s_mov_b32 s20, m0
	s_mov_b32 m0, s28
	s_nop 0
	global_load_lds_dwordx4 v227, s[8:9]
	s_mov_b32 m0, s20
	s_waitcnt vmcnt(9)
	s_waitcnt lgkmcnt(0)
	s_barrier
	s_setprio 1
	s_waitcnt lgkmcnt(7)
	v_mfma_f32_16x16x32_bf16 v[82:85], v[166:169], v[182:185], v[82:85]
	v_mfma_f32_16x16x32_bf16 v[78:81], v[174:177], v[182:185], v[78:81]
	s_waitcnt lgkmcnt(5)
	v_mfma_f32_16x16x32_bf16 v[74:77], v[166:169], v[190:193], v[74:77]
	v_mfma_f32_16x16x32_bf16 v[66:69], v[174:177], v[190:193], v[66:69]
	s_waitcnt lgkmcnt(3)
	v_mfma_f32_16x16x32_bf16 v[58:61], v[166:169], v[198:201], v[58:61]
	v_mfma_f32_16x16x32_bf16 v[50:53], v[174:177], v[198:201], v[50:53]
	s_waitcnt lgkmcnt(1)
	v_mfma_f32_16x16x32_bf16 v[42:45], v[166:169], v[206:209], v[42:45]
	v_mfma_f32_16x16x32_bf16 v[34:37], v[174:177], v[206:209], v[34:37]
	v_mfma_f32_16x16x32_bf16 v[82:85], v[170:173], v[186:189], v[82:85]
	v_mfma_f32_16x16x32_bf16 v[78:81], v[178:181], v[186:189], v[78:81]
	v_mfma_f32_16x16x32_bf16 v[74:77], v[170:173], v[194:197], v[74:77]
	v_mfma_f32_16x16x32_bf16 v[66:69], v[178:181], v[194:197], v[66:69]
	v_mfma_f32_16x16x32_bf16 v[58:61], v[170:173], v[202:205], v[58:61]
	v_mfma_f32_16x16x32_bf16 v[50:53], v[178:181], v[202:205], v[50:53]
	s_waitcnt lgkmcnt(0)
	v_mfma_f32_16x16x32_bf16 v[42:45], v[170:173], v[210:213], v[42:45]
	v_mfma_f32_16x16x32_bf16 v[34:37], v[178:181], v[210:213], v[34:37]
	s_setprio 0
	s_setprio 1
	v_mfma_f32_16x16x32_bf16 v[70:73], v[150:153], v[182:185], v[70:73]
	v_mfma_f32_16x16x32_bf16 v[62:65], v[158:161], v[182:185], v[62:65]
	v_mfma_f32_16x16x32_bf16 v[54:57], v[150:153], v[190:193], v[54:57]
	v_mfma_f32_16x16x32_bf16 v[46:49], v[158:161], v[190:193], v[46:49]
	v_mfma_f32_16x16x32_bf16 v[38:41], v[150:153], v[198:201], v[38:41]
	v_mfma_f32_16x16x32_bf16 v[30:33], v[158:161], v[198:201], v[30:33]
	v_mfma_f32_16x16x32_bf16 v[26:29], v[150:153], v[206:209], v[26:29]
	v_mfma_f32_16x16x32_bf16 v[22:25], v[158:161], v[206:209], v[22:25]
	v_mfma_f32_16x16x32_bf16 v[70:73], v[154:157], v[186:189], v[70:73]
	v_mfma_f32_16x16x32_bf16 v[62:65], v[162:165], v[186:189], v[62:65]
	v_mfma_f32_16x16x32_bf16 v[54:57], v[154:157], v[194:197], v[54:57]
	v_mfma_f32_16x16x32_bf16 v[46:49], v[162:165], v[194:197], v[46:49]
	v_mfma_f32_16x16x32_bf16 v[38:41], v[154:157], v[202:205], v[38:41]
	v_mfma_f32_16x16x32_bf16 v[30:33], v[162:165], v[202:205], v[30:33]
	v_mfma_f32_16x16x32_bf16 v[26:29], v[154:157], v[210:213], v[26:29]
	v_mfma_f32_16x16x32_bf16 v[22:25], v[162:165], v[210:213], v[22:25]
	s_setprio 0
	s_barrier
	v_add_u32_e32 v4, 0x18000, v234
	ds_read_b128 v[166:169], v4
	ds_read_b128 v[170:173], v4 offset:1024
	ds_read_b128 v[174:177], v4 offset:2048
	ds_read_b128 v[178:181], v4 offset:3072
	v_add_u32_e32 v4, 0x1c000, v234
	ds_read_b128 v[150:153], v4
	ds_read_b128 v[154:157], v4 offset:1024
	ds_read_b128 v[158:161], v4 offset:2048
	ds_read_b128 v[162:165], v4 offset:3072
	ds_read_b128 v[206:209], v235 offset:32768
	ds_read_b128 v[210:213], v235 offset:33792
	ds_read_b128 v[198:201], v235 offset:34816
	ds_read_b128 v[202:205], v235 offset:35840
	ds_read_b128 v[190:193], v235 offset:36864
	ds_read_b128 v[194:197], v235 offset:37888
	ds_read_b128 v[182:185], v235 offset:38912
	ds_read_b128 v[186:189], v235 offset:39936
	s_and_b64 vcc, exec, s[38:39]
	s_cbranch_vccnz .LBB0_1279
	v_xor_b32_e32 v6, 0x80, v2
	ds_read_b128 v[6:9], v6
	v_xor_b32_e32 v10, 0xc0, v2
	ds_read_b128 v[10:13], v10
